# router phases: the 9 later norm-gain/shift/scale loads per row pair (a serialized load-wait-store ladder) are pre-issued with the row loads; ladder waits removed
# speedup vs baseline: 1.0720x; 1.0102x over previous
.LBB0_641:
	v_ashrrev_i32_e32 v11, 31, v10
	v_lshlrev_b64 v[34:35], 11, v[10:11]
	v_lshl_add_u64 v[2:3], v[14:15], 0, v[34:35]
	global_load_dwordx2 v[40:41], v[2:3], off
	global_load_dwordx2 v[44:45], v[2:3], off offset:512
	global_load_dwordx2 v[46:47], v[2:3], off offset:1024
	global_load_dwordx2 v[48:49], v[2:3], off offset:1536
	s_waitcnt lgkmcnt(0)
	v_add_u32_e32 v4, 1, v10
	v_ashrrev_i32_e32 v5, 31, v4
	v_lshlrev_b64 v[60:61], 11, v[4:5]
	v_lshl_add_u64 v[2:3], v[14:15], 0, v[60:61]
	global_load_dwordx2 v[56:57], v[2:3], off
	global_load_dwordx2 v[58:59], v[2:3], off offset:512
	global_load_dwordx2 v[62:63], v[2:3], off offset:1024
	global_load_dwordx2 v[70:71], v[2:3], off offset:1536
	v_ashrrev_i32_e32 v32, 12, v10
	v_mul_hi_i32_i24_e32 v7, 0x6000, v32
	v_mul_i32_i24_e32 v6, 0x6000, v32
	s_mov_b64 s[4:5], 0x3000
	v_lshl_add_u64 v[6:7], s[44:45], 0, v[6:7]
	v_lshl_add_u64 v[54:55], v[6:7], 0, s[4:5]
	v_lshl_add_u64 v[42:43], v[6:7], 0, s[20:21]
	v_lshl_add_u64 v[6:7], v[54:55], 0, v[22:23]
	v_lshl_add_u64 v[36:37], v[42:43], 0, v[22:23]
	global_load_dwordx4 v[200:203], v[16:17], off offset:1024
	v_lshl_add_u64 v[236:237], v[42:43], 0, v[24:25]
	global_load_dwordx4 v[204:207], v[236:237], off
	v_lshl_add_u64 v[236:237], v[54:55], 0, v[24:25]
	global_load_dwordx4 v[208:211], v[236:237], off
	global_load_dwordx4 v[212:215], v[16:17], off offset:2048
	v_lshl_add_u64 v[236:237], v[42:43], 0, v[26:27]
	global_load_dwordx4 v[216:219], v[236:237], off
	v_lshl_add_u64 v[236:237], v[54:55], 0, v[26:27]
	global_load_dwordx4 v[220:223], v[236:237], off
	global_load_dwordx4 v[224:227], v[16:17], off offset:3072
	v_lshl_add_u64 v[236:237], v[42:43], 0, v[28:29]
	global_load_dwordx4 v[228:231], v[236:237], off
	v_lshl_add_u64 v[236:237], v[54:55], 0, v[28:29]
	global_load_dwordx4 v[232:235], v[236:237], off
	global_load_dwordx4 v[2:5], v[16:17], off
	s_nop 0
	global_load_dwordx4 v[6:9], v[6:7], off
	s_nop 0
	global_load_dwordx4 v[36:39], v[36:37], off
	v_lshl_add_u64 v[60:61], v[20:21], 0, v[60:61]
	s_waitcnt vmcnt(19)
	v_and_b32_e32 v75, 0xffff0000, v40
	s_waitcnt vmcnt(18)
	v_and_b32_e32 v79, 0xffff0000, v44
	s_waitcnt vmcnt(17)
	v_and_b32_e32 v83, 0xffff0000, v46
	s_waitcnt vmcnt(16)
	v_and_b32_e32 v53, 0xffff0000, v48
	v_lshlrev_b32_e32 v82, 16, v46
	v_lshlrev_b32_e32 v52, 16, v48
	v_mov_b32_e32 v96, v83
	v_mov_b32_e32 v97, v53
	v_lshlrev_b32_e32 v80, 16, v47
	v_lshlrev_b32_e32 v50, 16, v49
	v_mov_b32_e32 v94, v82
	v_mov_b32_e32 v95, v52
	v_pk_mul_f32 v[96:97], v[96:97], v[96:97]
	v_lshlrev_b32_e32 v74, 16, v40
	v_lshlrev_b32_e32 v76, 16, v45
	v_and_b32_e32 v77, 0xffff0000, v45
	v_lshlrev_b32_e32 v78, 16, v44
	v_and_b32_e32 v81, 0xffff0000, v47
	v_and_b32_e32 v51, 0xffff0000, v49
	s_waitcnt vmcnt(15)
	v_and_b32_e32 v45, 0xffff0000, v56
	v_mov_b32_e32 v84, v75
	v_mov_b32_e32 v85, v79
	s_waitcnt vmcnt(14)
	v_lshlrev_b32_e32 v86, 16, v59
	v_and_b32_e32 v87, 0xffff0000, v59
	v_lshlrev_b32_e32 v88, 16, v58
	v_and_b32_e32 v89, 0xffff0000, v58
	v_mov_b32_e32 v58, v80
	v_mov_b32_e32 v59, v50
	v_pk_fma_f32 v[94:95], v[94:95], v[94:95], v[96:97]
	v_lshlrev_b32_e32 v72, 16, v41
	v_and_b32_e32 v73, 0xffff0000, v41
	v_lshlrev_b32_e32 v40, 16, v57
	v_and_b32_e32 v41, 0xffff0000, v57
	v_lshlrev_b32_e32 v44, 16, v56
	v_mov_b32_e32 v56, v74
	v_mov_b32_e32 v57, v78
	s_waitcnt vmcnt(13)
	v_lshlrev_b32_e32 v90, 16, v63
	v_and_b32_e32 v91, 0xffff0000, v63
	v_lshlrev_b32_e32 v92, 16, v62
	v_and_b32_e32 v93, 0xffff0000, v62
	v_mov_b32_e32 v62, v81
	v_mov_b32_e32 v63, v51
	v_pk_mul_f32 v[84:85], v[84:85], v[84:85]
	v_mov_b32_e32 v104, v45
	v_mov_b32_e32 v105, v89
	v_pk_fma_f32 v[58:59], v[58:59], v[58:59], v[94:95]
	v_mov_b32_e32 v46, v72
	v_mov_b32_e32 v47, v76
	v_mov_b32_e32 v102, v44
	v_mov_b32_e32 v103, v88
	v_pk_fma_f32 v[56:57], v[56:57], v[56:57], v[84:85]
	v_pk_mul_f32 v[84:85], v[104:105], v[104:105]
	v_pk_fma_f32 v[58:59], v[62:63], v[62:63], v[58:59]
	s_waitcnt vmcnt(12)
	v_and_b32_e32 v63, 0xffff0000, v70
	v_mov_b32_e32 v48, v73
	v_mov_b32_e32 v49, v77
	v_mov_b32_e32 v98, v40
	v_mov_b32_e32 v99, v86
	v_pk_fma_f32 v[46:47], v[46:47], v[46:47], v[56:57]
	v_pk_fma_f32 v[56:57], v[102:103], v[102:103], v[84:85]
	v_lshlrev_b32_e32 v62, 16, v70
	v_mov_b32_e32 v96, v93
	v_mov_b32_e32 v97, v63
	v_pk_fma_f32 v[46:47], v[48:49], v[48:49], v[46:47]
	v_pk_fma_f32 v[48:49], v[98:99], v[98:99], v[56:57]
	v_lshlrev_b32_e32 v56, 16, v71
	v_mov_b32_e32 v94, v92
	v_mov_b32_e32 v95, v62
	v_pk_mul_f32 v[96:97], v[96:97], v[96:97]
	v_mov_b32_e32 v100, v41
	v_mov_b32_e32 v101, v87
	v_and_b32_e32 v57, 0xffff0000, v71
	v_mov_b32_e32 v70, v90
	v_mov_b32_e32 v71, v56
	v_pk_fma_f32 v[94:95], v[94:95], v[94:95], v[96:97]
	v_pk_fma_f32 v[48:49], v[100:101], v[100:101], v[48:49]
	v_mov_b32_e32 v84, v91
	v_mov_b32_e32 v85, v57
	v_pk_fma_f32 v[70:71], v[70:71], v[70:71], v[94:95]
	s_waitcnt vmcnt(0)
	v_pk_add_f32 v[38:39], v[38:39], 1.0 op_sel_hi:[1,0]
	v_pk_fma_f32 v[70:71], v[84:85], v[84:85], v[70:71]
	v_mov_b32_e32 v84, v48
	v_mov_b32_e32 v85, v46
	v_mov_b32_e32 v46, v49
	v_pk_add_f32 v[46:47], v[84:85], v[46:47]
	v_mov_b32_e32 v48, v70
	v_mov_b32_e32 v49, v58
	v_pk_add_f32 v[46:47], v[46:47], v[48:49]
	v_mov_b32_e32 v58, v71
	v_pk_add_f32 v[46:47], v[46:47], v[58:59]
	ds_bpermute_b32 v49, v1, v47
	ds_bpermute_b32 v48, v1, v46
	v_pk_add_f32 v[70:71], v[36:37], 1.0 op_sel_hi:[1,0]
	v_lshl_add_u64 v[58:59], v[20:21], 0, v[34:35]
	s_waitcnt lgkmcnt(0)
	v_pk_add_f32 v[46:47], v[46:47], v[48:49]
	ds_bpermute_b32 v49, v31, v47
	ds_bpermute_b32 v48, v31, v46
	s_waitcnt lgkmcnt(0)
	v_pk_add_f32 v[46:47], v[46:47], v[48:49]
	ds_bpermute_b32 v49, v64, v47
	ds_bpermute_b32 v48, v64, v46
	s_waitcnt lgkmcnt(0)
	v_pk_add_f32 v[46:47], v[46:47], v[48:49]
	ds_bpermute_b32 v49, v65, v47
	ds_bpermute_b32 v48, v65, v46
	s_waitcnt lgkmcnt(0)
	v_pk_add_f32 v[46:47], v[46:47], v[48:49]
	ds_bpermute_b32 v49, v66, v47
	ds_bpermute_b32 v48, v66, v46
	s_waitcnt lgkmcnt(0)
	v_pk_add_f32 v[46:47], v[46:47], v[48:49]
	ds_bpermute_b32 v49, v67, v47
	ds_bpermute_b32 v48, v67, v46
	s_waitcnt lgkmcnt(0)
	v_pk_add_f32 v[36:37], v[46:47], v[48:49]
	s_nop 0
	v_pk_fma_f32 v[46:47], v[36:37], s[22:23], v[30:31] op_sel_hi:[1,0,0]
	v_lshl_add_u64 v[48:49], v[42:43], 0, v[24:25]
	v_mul_f32_e32 v11, 0x4b800000, v47
	v_cmp_gt_f32_e32 vcc, s24, v47
	s_nop 1
	v_cndmask_b32_e32 v11, v47, v11, vcc
	v_rsq_f32_e32 v11, v11
	s_nop 0
	v_mul_f32_e32 v12, 0x45800000, v11
	v_cndmask_b32_e32 v12, v11, v12, vcc
	v_mul_f32_e32 v11, 0x4b800000, v46
	v_cmp_gt_f32_e32 vcc, s24, v46
	v_pk_mul_f32 v[34:35], v[12:13], v[74:75] op_sel_hi:[0,1]
	v_pk_mul_f32 v[34:35], v[2:3], v[34:35]
	v_cndmask_b32_e32 v11, v46, v11, vcc
	v_rsq_f32_e32 v11, v11
	v_pk_fma_f32 v[36:37], v[70:71], v[34:35], v[6:7]
	v_pk_mul_f32 v[34:35], v[12:13], v[72:73] op_sel_hi:[0,1]
	v_pk_mul_f32 v[34:35], v[4:5], v[34:35]
	v_mul_f32_e32 v33, 0x45800000, v11
	v_cndmask_b32_e32 v114, v11, v33, vcc
	v_pk_mul_f32 v[44:45], v[114:115], v[44:45] op_sel_hi:[0,1]
	v_pk_mul_f32 v[2:3], v[2:3], v[44:45]
	v_pk_fma_f32 v[34:35], v[38:39], v[34:35], v[8:9]
	v_pk_fma_f32 v[6:7], v[70:71], v[2:3], v[6:7]
	v_pk_mul_f32 v[2:3], v[114:115], v[40:41] op_sel_hi:[0,1]
	v_pk_mul_f32 v[2:3], v[4:5], v[2:3]
	v_cvt_pk_bf16_f32 v46, v36, v37
	v_pk_fma_f32 v[2:3], v[38:39], v[2:3], v[8:9]
	v_cvt_pk_bf16_f32 v47, v34, v35
	v_cvt_pk_bf16_f32 v4, v6, v7
	v_cvt_pk_bf16_f32 v5, v2, v3
	global_store_dwordx2 v[58:59], v[46:47], off
	global_store_dwordx2 v[60:61], v[4:5], off
	v_mov_b32_e32 v38, v200
	v_mov_b32_e32 v39, v201
	v_mov_b32_e32 v40, v202
	v_mov_b32_e32 v41, v203
	s_nop 0
	v_mov_b32_e32 v44, v204
	v_mov_b32_e32 v45, v205
	v_mov_b32_e32 v46, v206
	v_mov_b32_e32 v47, v207
	v_lshl_add_u64 v[4:5], v[54:55], 0, v[24:25]
	v_mov_b32_e32 v70, v208
	v_mov_b32_e32 v71, v209
	v_mov_b32_e32 v72, v210
	v_mov_b32_e32 v73, v211
	v_pk_mul_f32 v[4:5], v[12:13], v[78:79] op_sel_hi:[0,1]
	v_pk_mul_f32 v[8:9], v[12:13], v[76:77] op_sel_hi:[0,1]
	v_pk_mul_f32 v[74:75], v[114:115], v[88:89] op_sel_hi:[0,1]
	v_pk_mul_f32 v[76:77], v[114:115], v[86:87] op_sel_hi:[0,1]
	v_lshl_add_u64 v[48:49], v[42:43], 0, v[26:27]
	v_lshl_add_u64 v[78:79], v[42:43], 0, v[28:29]
	v_pk_mul_f32 v[42:43], v[12:13], v[82:83] op_sel_hi:[0,1]
	v_pk_mul_f32 v[82:83], v[114:115], v[90:91] op_sel_hi:[0,1]
	v_pk_mul_f32 v[52:53], v[12:13], v[52:53] op_sel_hi:[0,1]
	v_pk_mul_f32 v[50:51], v[12:13], v[50:51] op_sel_hi:[0,1]
	v_pk_mul_f32 v[56:57], v[114:115], v[56:57] op_sel_hi:[0,1]
	v_pk_mul_f32 v[4:5], v[38:39], v[4:5]
	v_pk_add_f32 v[44:45], v[44:45], 1.0 op_sel_hi:[1,0]
	v_pk_mul_f32 v[8:9], v[40:41], v[8:9]
	v_pk_add_f32 v[46:47], v[46:47], 1.0 op_sel_hi:[1,0]
	v_pk_mul_f32 v[74:75], v[38:39], v[74:75]
	v_pk_mul_f32 v[76:77], v[40:41], v[76:77]
	v_pk_fma_f32 v[40:41], v[4:5], v[44:45], v[70:71]
	v_pk_fma_f32 v[38:39], v[8:9], v[46:47], v[72:73]
	v_pk_fma_f32 v[8:9], v[44:45], v[74:75], v[70:71]
	v_pk_fma_f32 v[4:5], v[46:47], v[76:77], v[72:73]
	v_cvt_pk_bf16_f32 v44, v40, v41
	v_cvt_pk_bf16_f32 v45, v38, v39
	v_cvt_pk_bf16_f32 v46, v8, v9
	v_cvt_pk_bf16_f32 v47, v4, v5
	global_store_dwordx2 v[58:59], v[44:45], off offset:512
	global_store_dwordx2 v[60:61], v[46:47], off offset:512
	v_mov_b32_e32 v44, v212
	v_mov_b32_e32 v45, v213
	v_mov_b32_e32 v46, v214
	v_mov_b32_e32 v47, v215
	s_nop 0
	v_mov_b32_e32 v70, v216
	v_mov_b32_e32 v71, v217
	v_mov_b32_e32 v72, v218
	v_mov_b32_e32 v73, v219
	v_lshl_add_u64 v[48:49], v[54:55], 0, v[26:27]
	v_mov_b32_e32 v74, v220
	v_mov_b32_e32 v75, v221
	v_mov_b32_e32 v76, v222
	v_mov_b32_e32 v77, v223
	v_pk_mul_f32 v[48:49], v[12:13], v[80:81] op_sel_hi:[0,1]
	v_pk_mul_f32 v[80:81], v[114:115], v[92:93] op_sel_hi:[0,1]
	v_lshl_add_u64 v[54:55], v[54:55], 0, v[28:29]
	v_pk_mul_f32 v[42:43], v[42:43], v[44:45]
	v_pk_add_f32 v[70:71], v[70:71], 1.0 op_sel_hi:[1,0]
	v_pk_mul_f32 v[84:85], v[48:49], v[46:47]
	v_pk_add_f32 v[72:73], v[72:73], 1.0 op_sel_hi:[1,0]
	v_pk_mul_f32 v[44:45], v[80:81], v[44:45]
	v_pk_mul_f32 v[80:81], v[82:83], v[46:47]
	v_pk_fma_f32 v[48:49], v[42:43], v[70:71], v[74:75]
	v_pk_fma_f32 v[46:47], v[84:85], v[72:73], v[76:77]
	v_pk_fma_f32 v[44:45], v[44:45], v[70:71], v[74:75]
	v_pk_fma_f32 v[42:43], v[80:81], v[72:73], v[76:77]
	v_cvt_pk_bf16_f32 v70, v48, v49
	v_cvt_pk_bf16_f32 v71, v46, v47
	v_cvt_pk_bf16_f32 v72, v44, v45
	v_cvt_pk_bf16_f32 v73, v42, v43
	global_store_dwordx2 v[58:59], v[70:71], off offset:1024
	global_store_dwordx2 v[60:61], v[72:73], off offset:1024
	v_mov_b32_e32 v70, v224
	v_mov_b32_e32 v71, v225
	v_mov_b32_e32 v72, v226
	v_mov_b32_e32 v73, v227
	s_nop 0
	v_mov_b32_e32 v74, v228
	v_mov_b32_e32 v75, v229
	v_mov_b32_e32 v76, v230
	v_mov_b32_e32 v77, v231
	v_pk_mul_f32 v[52:53], v[52:53], v[70:71]
	v_mov_b32_e32 v78, v232
	v_mov_b32_e32 v79, v233
	v_mov_b32_e32 v80, v234
	v_mov_b32_e32 v81, v235
	ds_read_b128 v[82:85], v68
	ds_read_b128 v[86:89], v68 offset:1024
	ds_read_b128 v[90:93], v68 offset:2048
	ds_read_b128 v[94:97], v68 offset:3072
	ds_read_b128 v[98:101], v68 offset:7168
	ds_read_b128 v[102:105], v68 offset:6144
	ds_read_b128 v[106:109], v68 offset:5120
	ds_read_b128 v[110:113], v68 offset:4096
	s_waitcnt lgkmcnt(7)
	v_mul_f32_e32 v11, v37, v83
	v_mul_f32_e32 v12, v7, v83
	v_pk_mul_f32 v[54:55], v[114:115], v[62:63] op_sel_hi:[0,1]
	v_fmac_f32_e32 v11, v36, v82
	s_waitcnt lgkmcnt(0)
	v_mul_f32_e32 v33, v37, v111
	v_mul_f32_e32 v62, v7, v111
	v_fmac_f32_e32 v12, v6, v82
	v_fmac_f32_e32 v33, v36, v110
	v_fmac_f32_e32 v62, v6, v110
	v_fmac_f32_e32 v11, v34, v84
	v_fmac_f32_e32 v12, v2, v84
	v_mul_f32_e32 v63, v41, v87
	v_mul_f32_e32 v83, v41, v107
	v_mul_f32_e32 v84, v9, v107
	v_fmac_f32_e32 v33, v34, v112
	v_fmac_f32_e32 v62, v2, v112
	v_fmac_f32_e32 v63, v40, v86
	v_fmac_f32_e32 v83, v40, v106
	v_fmac_f32_e32 v84, v8, v106
	v_fmac_f32_e32 v11, v35, v85
	v_fmac_f32_e32 v33, v35, v113
	v_fmac_f32_e32 v62, v3, v113
	v_mul_f32_e32 v82, v9, v87
	v_fmac_f32_e32 v63, v38, v88
	v_fmac_f32_e32 v83, v38, v108
	v_fmac_f32_e32 v84, v4, v108
	v_add_f32_e32 v11, 0, v11
	v_add_f32_e32 v33, 0, v33
	v_add_f32_e32 v62, 0, v62
	v_fmac_f32_e32 v82, v8, v86
	v_fmac_f32_e32 v63, v39, v89
	v_fmac_f32_e32 v83, v39, v109
	v_fmac_f32_e32 v84, v5, v109
	v_fmac_f32_e32 v12, v3, v85
	v_fmac_f32_e32 v82, v4, v88
	v_add_f32_e32 v11, v11, v63
	v_add_f32_e32 v33, v83, v33
	v_add_f32_e32 v62, v84, v62
	v_mul_f32_e32 v63, v49, v91
	v_mul_f32_e32 v83, v49, v103
	v_mul_f32_e32 v84, v45, v103
	v_add_f32_e32 v12, 0, v12
	v_fmac_f32_e32 v82, v5, v89
	v_fmac_f32_e32 v63, v48, v90
	v_fmac_f32_e32 v83, v48, v102
	v_fmac_f32_e32 v84, v44, v102
	v_add_f32_e32 v12, v12, v82
	v_mul_f32_e32 v82, v45, v91
	v_fmac_f32_e32 v63, v46, v92
	v_fmac_f32_e32 v83, v46, v104
	v_fmac_f32_e32 v84, v42, v104
	v_fmac_f32_e32 v82, v44, v90
	v_fmac_f32_e32 v63, v47, v93
	v_fmac_f32_e32 v83, v47, v105
	v_fmac_f32_e32 v84, v43, v105
	v_fmac_f32_e32 v82, v42, v92
	v_add_f32_e32 v11, v11, v63
	v_add_f32_e32 v33, v83, v33
	v_add_f32_e32 v83, v84, v62
	v_pk_add_f32 v[62:63], v[74:75], 1.0 op_sel_hi:[1,0]
	v_pk_mul_f32 v[70:71], v[54:55], v[70:71]
	v_fmac_f32_e32 v82, v43, v93
	v_pk_mul_f32 v[50:51], v[50:51], v[72:73]
	v_pk_add_f32 v[74:75], v[76:77], 1.0 op_sel_hi:[1,0]
	v_pk_mul_f32 v[72:73], v[56:57], v[72:73]
	v_add_f32_e32 v82, v12, v82
	v_pk_fma_f32 v[56:57], v[52:53], v[62:63], v[78:79]
	v_pk_fma_f32 v[52:53], v[70:71], v[62:63], v[78:79]
	v_pk_fma_f32 v[54:55], v[50:51], v[74:75], v[80:81]
	v_pk_fma_f32 v[50:51], v[72:73], v[74:75], v[80:81]
	v_mul_f32_e32 v12, v57, v95
	v_mul_f32_e32 v72, v53, v95
	v_mul_f32_e32 v73, v57, v99
	v_mul_f32_e32 v74, v53, v99
	v_fmac_f32_e32 v12, v56, v94
	v_fmac_f32_e32 v72, v52, v94
	v_fmac_f32_e32 v73, v56, v98
	v_fmac_f32_e32 v74, v52, v98
	v_fmac_f32_e32 v12, v54, v96
	v_fmac_f32_e32 v72, v50, v96
	v_fmac_f32_e32 v73, v54, v100
	v_fmac_f32_e32 v74, v50, v100
	v_cvt_pk_bf16_f32 v62, v56, v57
	v_cvt_pk_bf16_f32 v63, v54, v55
	v_fmac_f32_e32 v12, v55, v97
	v_fmac_f32_e32 v72, v51, v97
	v_fmac_f32_e32 v73, v55, v101
	v_fmac_f32_e32 v74, v51, v101
	v_cvt_pk_bf16_f32 v70, v52, v53
	v_cvt_pk_bf16_f32 v71, v50, v51
	global_store_dwordx2 v[58:59], v[62:63], off offset:1536
	global_store_dwordx2 v[60:61], v[70:71], off offset:1536
	v_add_f32_e32 v12, v11, v12
	v_add_f32_e32 v58, v82, v72
	v_add_f32_e32 v11, v73, v33
	v_add_f32_e32 v33, v74, v83
	ds_read_b128 v[60:63], v68 offset:8192
	ds_read_b128 v[70:73], v68 offset:9216
	s_waitcnt lgkmcnt(1)
	v_mul_f32_e32 v59, v37, v61
	v_mul_f32_e32 v61, v7, v61
	v_fmac_f32_e32 v59, v36, v60
	v_fmac_f32_e32 v61, v6, v60
	s_waitcnt lgkmcnt(0)
	v_mul_f32_e32 v60, v41, v71
	v_fmac_f32_e32 v59, v34, v62
	v_fmac_f32_e32 v60, v40, v70
	v_fmac_f32_e32 v61, v2, v62
	v_fmac_f32_e32 v59, v35, v63
	v_fmac_f32_e32 v60, v38, v72
	v_add_f32_e32 v59, 0, v59
	v_fmac_f32_e32 v61, v3, v63
	v_fmac_f32_e32 v60, v39, v73
	v_add_f32_e32 v74, 0, v61
	v_add_f32_e32 v59, v59, v60
	v_mul_f32_e32 v71, v9, v71
	ds_read_b128 v[60:63], v68 offset:10240
	v_fmac_f32_e32 v71, v8, v70
	v_fmac_f32_e32 v71, v4, v72
	v_fmac_f32_e32 v71, v5, v73
	v_add_f32_e32 v74, v74, v71
	ds_read_b128 v[70:73], v68 offset:11264
	s_waitcnt lgkmcnt(1)
	v_mul_f32_e32 v75, v49, v61
	v_mul_f32_e32 v61, v45, v61
	v_fmac_f32_e32 v61, v44, v60
	v_fmac_f32_e32 v61, v42, v62
	v_fmac_f32_e32 v61, v43, v63
	v_fmac_f32_e32 v75, v48, v60
	v_add_f32_e32 v60, v74, v61
	s_waitcnt lgkmcnt(0)
	v_mul_f32_e32 v61, v57, v71
	v_fmac_f32_e32 v75, v46, v62
	v_fmac_f32_e32 v61, v56, v70
	v_fmac_f32_e32 v75, v47, v63
	v_fmac_f32_e32 v61, v54, v72
	v_add_f32_e32 v59, v59, v75
	v_fmac_f32_e32 v61, v55, v73
	ds_read_b128 v[74:77], v68 offset:13312
	ds_read_b128 v[78:81], v68 offset:12288
	v_add_f32_e32 v59, v59, v61
	v_mul_f32_e32 v61, v53, v71
	v_fmac_f32_e32 v61, v52, v70
	v_fmac_f32_e32 v61, v50, v72
	v_fmac_f32_e32 v61, v51, v73
	v_add_f32_e32 v60, v60, v61
	s_waitcnt lgkmcnt(0)
	v_mul_f32_e32 v61, v37, v79
	v_fmac_f32_e32 v61, v36, v78
	v_mul_f32_e32 v63, v41, v75
	v_fmac_f32_e32 v61, v34, v80
	v_fmac_f32_e32 v63, v40, v74
	v_fmac_f32_e32 v61, v35, v81
	v_fmac_f32_e32 v63, v38, v76
	ds_read_b128 v[70:73], v68 offset:15360
	ds_read_b128 v[82:85], v68 offset:14336
	v_add_f32_e32 v61, 0, v61
	v_mul_f32_e32 v62, v7, v79
	v_fmac_f32_e32 v63, v39, v77
	v_fmac_f32_e32 v62, v6, v78
	v_add_f32_e32 v61, v63, v61
	v_mul_f32_e32 v63, v9, v75
	v_fmac_f32_e32 v62, v2, v80
	v_fmac_f32_e32 v63, v8, v74
	v_fmac_f32_e32 v62, v3, v81
	v_fmac_f32_e32 v63, v4, v76
	v_add_f32_e32 v62, 0, v62
	v_fmac_f32_e32 v63, v5, v77
	v_add_f32_e32 v62, v63, v62
	s_waitcnt lgkmcnt(0)
	v_mul_f32_e32 v63, v49, v83
	v_fmac_f32_e32 v63, v48, v82
	v_fmac_f32_e32 v63, v46, v84
	v_fmac_f32_e32 v63, v47, v85
	v_add_f32_e32 v61, v63, v61
	v_mul_f32_e32 v63, v45, v83
	v_fmac_f32_e32 v63, v44, v82
	v_fmac_f32_e32 v63, v42, v84
	v_fmac_f32_e32 v63, v43, v85
	v_add_f32_e32 v62, v63, v62
	v_mul_f32_e32 v63, v57, v71
	v_fmac_f32_e32 v63, v56, v70
	v_fmac_f32_e32 v63, v54, v72
	v_fmac_f32_e32 v63, v55, v73
	v_add_f32_e32 v61, v63, v61
	v_mul_f32_e32 v63, v53, v71
	v_fmac_f32_e32 v63, v52, v70
	v_fmac_f32_e32 v63, v50, v72
	v_fmac_f32_e32 v63, v51, v73
	v_add_f32_e32 v62, v63, v62
	ds_read_b128 v[70:73], v68 offset:16384
	ds_read_b128 v[74:77], v68 offset:17408
	s_waitcnt lgkmcnt(1)
	v_mul_f32_e32 v63, v37, v71
	v_mul_f32_e32 v71, v7, v71
	v_fmac_f32_e32 v63, v36, v70
	v_fmac_f32_e32 v71, v6, v70
	s_waitcnt lgkmcnt(0)
	v_mul_f32_e32 v70, v41, v75
	v_fmac_f32_e32 v63, v34, v72
	v_fmac_f32_e32 v70, v40, v74
	v_fmac_f32_e32 v71, v2, v72
	v_fmac_f32_e32 v63, v35, v73
	v_fmac_f32_e32 v70, v38, v76
	v_add_f32_e32 v63, 0, v63
	v_fmac_f32_e32 v71, v3, v73
	v_fmac_f32_e32 v70, v39, v77
	v_add_f32_e32 v78, 0, v71
	v_add_f32_e32 v63, v63, v70
	v_mul_f32_e32 v75, v9, v75
	ds_read_b128 v[70:73], v68 offset:18432
	v_fmac_f32_e32 v75, v8, v74
	v_fmac_f32_e32 v75, v4, v76
	v_fmac_f32_e32 v75, v5, v77
	v_add_f32_e32 v78, v78, v75
	ds_read_b128 v[74:77], v68 offset:19456
	s_waitcnt lgkmcnt(1)
	v_mul_f32_e32 v79, v49, v71
	v_mul_f32_e32 v71, v45, v71
	v_fmac_f32_e32 v71, v44, v70
	v_fmac_f32_e32 v71, v42, v72
	v_fmac_f32_e32 v71, v43, v73
	v_fmac_f32_e32 v79, v48, v70
	v_add_f32_e32 v70, v78, v71
	s_waitcnt lgkmcnt(0)
	v_mul_f32_e32 v71, v57, v75
	v_fmac_f32_e32 v79, v46, v72
	v_fmac_f32_e32 v71, v56, v74
	v_fmac_f32_e32 v79, v47, v73
	v_fmac_f32_e32 v71, v54, v76
	v_add_f32_e32 v63, v63, v79
	v_fmac_f32_e32 v71, v55, v77
	v_add_f32_e32 v63, v63, v71
	v_mul_f32_e32 v71, v53, v75
	v_fmac_f32_e32 v71, v52, v74
	ds_read_b128 v[72:75], v68 offset:21504
	ds_read_b128 v[78:81], v68 offset:20480
	v_fmac_f32_e32 v71, v50, v76
	ds_read_b128 v[82:85], v68 offset:23552
	ds_read_b128 v[86:89], v68 offset:22528
	v_fmac_f32_e32 v71, v51, v77
	s_waitcnt lgkmcnt(3)
	v_mul_f32_e32 v77, v41, v73
	s_waitcnt lgkmcnt(2)
	v_mul_f32_e32 v76, v7, v79
	v_fmac_f32_e32 v76, v6, v78
	v_mul_f32_e32 v73, v9, v73
	v_fmac_f32_e32 v76, v2, v80
	v_fmac_f32_e32 v73, v8, v72
	v_add_f32_e32 v70, v70, v71
	v_mul_f32_e32 v71, v37, v79
	v_fmac_f32_e32 v76, v3, v81
	v_fmac_f32_e32 v73, v4, v74
	v_fmac_f32_e32 v71, v36, v78
	v_add_f32_e32 v76, 0, v76
	v_fmac_f32_e32 v73, v5, v75
	v_fmac_f32_e32 v71, v34, v80
	v_fmac_f32_e32 v77, v40, v72
	v_add_f32_e32 v72, v73, v76
	s_waitcnt lgkmcnt(0)
	v_mul_f32_e32 v73, v49, v87
	v_fmac_f32_e32 v71, v35, v81
	v_fmac_f32_e32 v77, v38, v74
	v_fmac_f32_e32 v73, v48, v86
	v_add_f32_e32 v71, 0, v71
	v_fmac_f32_e32 v77, v39, v75
	v_fmac_f32_e32 v73, v46, v88
	v_add_f32_e32 v71, v77, v71
	v_fmac_f32_e32 v73, v47, v89
	v_add_f32_e32 v71, v73, v71
	v_mul_f32_e32 v73, v45, v87
	v_fmac_f32_e32 v73, v44, v86
	v_fmac_f32_e32 v73, v42, v88
	v_fmac_f32_e32 v73, v43, v89
	v_add_f32_e32 v72, v73, v72
	v_mul_f32_e32 v73, v57, v83
	v_fmac_f32_e32 v73, v56, v82
	v_fmac_f32_e32 v73, v54, v84
	v_fmac_f32_e32 v73, v55, v85
	v_add_f32_e32 v71, v73, v71
	v_mul_f32_e32 v73, v53, v83
	v_fmac_f32_e32 v73, v52, v82
	v_fmac_f32_e32 v73, v50, v84
	v_fmac_f32_e32 v73, v51, v85
	v_add_f32_e32 v72, v73, v72
	ds_read_b128 v[74:77], v68 offset:24576
	ds_read_b128 v[78:81], v68 offset:25600
	s_waitcnt lgkmcnt(1)
	v_mul_f32_e32 v73, v37, v75
	v_mul_f32_e32 v75, v7, v75
	v_fmac_f32_e32 v73, v36, v74
	v_fmac_f32_e32 v75, v6, v74
	s_waitcnt lgkmcnt(0)
	v_mul_f32_e32 v74, v41, v79
	v_fmac_f32_e32 v73, v34, v76
	v_fmac_f32_e32 v74, v40, v78
	v_fmac_f32_e32 v75, v2, v76
	v_fmac_f32_e32 v73, v35, v77
	v_fmac_f32_e32 v74, v38, v80
	v_add_f32_e32 v73, 0, v73
	v_fmac_f32_e32 v75, v3, v77
	v_fmac_f32_e32 v74, v39, v81
	v_add_f32_e32 v82, 0, v75
	v_add_f32_e32 v73, v73, v74
	v_mul_f32_e32 v79, v9, v79
	ds_read_b128 v[74:77], v68 offset:26624
	v_fmac_f32_e32 v79, v8, v78
	v_fmac_f32_e32 v79, v4, v80
	v_fmac_f32_e32 v79, v5, v81
	v_add_f32_e32 v82, v82, v79
	ds_read_b128 v[78:81], v68 offset:27648
	s_waitcnt lgkmcnt(1)
	v_mul_f32_e32 v83, v49, v75
	v_mul_f32_e32 v75, v45, v75
	v_fmac_f32_e32 v75, v44, v74
	v_fmac_f32_e32 v75, v42, v76
	v_fmac_f32_e32 v75, v43, v77
	v_fmac_f32_e32 v83, v48, v74
	v_add_f32_e32 v74, v82, v75
	s_waitcnt lgkmcnt(0)
	v_mul_f32_e32 v75, v57, v79
	v_fmac_f32_e32 v83, v46, v76
	v_fmac_f32_e32 v75, v56, v78
	v_fmac_f32_e32 v83, v47, v77
	v_fmac_f32_e32 v75, v54, v80
	v_add_f32_e32 v73, v73, v83
	v_fmac_f32_e32 v75, v55, v81
	v_add_f32_e32 v73, v73, v75
	v_mul_f32_e32 v75, v53, v79
	v_fmac_f32_e32 v75, v52, v78
	ds_read_b128 v[76:79], v68 offset:29696
	ds_read_b128 v[82:85], v68 offset:28672
	v_fmac_f32_e32 v75, v50, v80
	ds_read_b128 v[86:89], v68 offset:31744
	ds_read_b128 v[90:93], v68 offset:30720
	v_fmac_f32_e32 v75, v51, v81
	s_waitcnt lgkmcnt(3)
	v_mul_f32_e32 v81, v41, v77
	s_waitcnt lgkmcnt(2)
	v_mul_f32_e32 v80, v7, v83
	v_fmac_f32_e32 v80, v6, v82
	v_mul_f32_e32 v77, v9, v77
	v_fmac_f32_e32 v80, v2, v84
	v_fmac_f32_e32 v77, v8, v76
	v_add_f32_e32 v74, v74, v75
	v_mul_f32_e32 v75, v37, v83
	v_fmac_f32_e32 v80, v3, v85
	v_fmac_f32_e32 v77, v4, v78
	v_fmac_f32_e32 v75, v36, v82
	v_add_f32_e32 v80, 0, v80
	v_fmac_f32_e32 v77, v5, v79
	v_fmac_f32_e32 v75, v34, v84
	v_fmac_f32_e32 v81, v40, v76
	v_add_f32_e32 v76, v77, v80
	s_waitcnt lgkmcnt(0)
	v_mul_f32_e32 v77, v49, v91
	v_fmac_f32_e32 v75, v35, v85
	v_fmac_f32_e32 v81, v38, v78
	v_fmac_f32_e32 v77, v48, v90
	v_add_f32_e32 v75, 0, v75
	v_fmac_f32_e32 v81, v39, v79
	v_fmac_f32_e32 v77, v46, v92
	v_add_f32_e32 v75, v81, v75
	v_fmac_f32_e32 v77, v47, v93
	v_add_f32_e32 v75, v77, v75
	v_mul_f32_e32 v77, v45, v91
	v_fmac_f32_e32 v77, v44, v90
	v_fmac_f32_e32 v77, v42, v92
	v_fmac_f32_e32 v77, v43, v93
	v_add_f32_e32 v76, v77, v76
	v_mul_f32_e32 v77, v57, v87
	v_fmac_f32_e32 v77, v56, v86
	v_fmac_f32_e32 v77, v54, v88
	v_fmac_f32_e32 v77, v55, v89
	v_add_f32_e32 v75, v77, v75
	v_mul_f32_e32 v77, v53, v87
	v_fmac_f32_e32 v77, v52, v86
	v_fmac_f32_e32 v77, v50, v88
	v_fmac_f32_e32 v77, v51, v89
	v_add_f32_e32 v76, v77, v76
	ds_read_b128 v[78:81], v68 offset:32768
	ds_read_b128 v[82:85], v68 offset:33792
	s_waitcnt lgkmcnt(1)
	v_mul_f32_e32 v77, v37, v79
	v_mul_f32_e32 v79, v7, v79
	v_fmac_f32_e32 v77, v36, v78
	v_fmac_f32_e32 v79, v6, v78
	s_waitcnt lgkmcnt(0)
	v_mul_f32_e32 v78, v41, v83
	v_fmac_f32_e32 v77, v34, v80
	v_fmac_f32_e32 v78, v40, v82
	v_fmac_f32_e32 v79, v2, v80
	v_fmac_f32_e32 v77, v35, v81
	v_fmac_f32_e32 v78, v38, v84
	v_add_f32_e32 v77, 0, v77
	v_fmac_f32_e32 v79, v3, v81
	v_fmac_f32_e32 v78, v39, v85
	v_add_f32_e32 v86, 0, v79
	v_add_f32_e32 v77, v77, v78
	v_mul_f32_e32 v83, v9, v83
	ds_read_b128 v[78:81], v68 offset:34816
	v_fmac_f32_e32 v83, v8, v82
	v_fmac_f32_e32 v83, v4, v84
	v_fmac_f32_e32 v83, v5, v85
	v_add_f32_e32 v86, v86, v83
	ds_read_b128 v[82:85], v68 offset:35840
	s_waitcnt lgkmcnt(1)
	v_mul_f32_e32 v87, v49, v79
	v_mul_f32_e32 v79, v45, v79
	v_fmac_f32_e32 v79, v44, v78
	v_fmac_f32_e32 v79, v42, v80
	v_fmac_f32_e32 v79, v43, v81
	v_fmac_f32_e32 v87, v48, v78
	v_add_f32_e32 v78, v86, v79
	s_waitcnt lgkmcnt(0)
	v_mul_f32_e32 v79, v57, v83
	v_fmac_f32_e32 v87, v46, v80
	v_fmac_f32_e32 v79, v56, v82
	v_fmac_f32_e32 v87, v47, v81
	v_fmac_f32_e32 v79, v54, v84
	v_add_f32_e32 v77, v77, v87
	v_fmac_f32_e32 v79, v55, v85
	v_add_f32_e32 v77, v77, v79
	v_mul_f32_e32 v79, v53, v83
	v_fmac_f32_e32 v79, v52, v82
	ds_read_b128 v[80:83], v68 offset:37888
	ds_read_b128 v[86:89], v68 offset:36864
	v_fmac_f32_e32 v79, v50, v84
	ds_read_b128 v[90:93], v68 offset:39936
	ds_read_b128 v[94:97], v68 offset:38912
	v_fmac_f32_e32 v79, v51, v85
	s_waitcnt lgkmcnt(3)
	v_mul_f32_e32 v85, v41, v81
	s_waitcnt lgkmcnt(2)
	v_mul_f32_e32 v84, v7, v87
	v_fmac_f32_e32 v84, v6, v86
	v_mul_f32_e32 v81, v9, v81
	v_fmac_f32_e32 v84, v2, v88
	v_fmac_f32_e32 v81, v8, v80
	v_add_f32_e32 v78, v78, v79
	v_mul_f32_e32 v79, v37, v87
	v_fmac_f32_e32 v84, v3, v89
	v_fmac_f32_e32 v81, v4, v82
	v_fmac_f32_e32 v79, v36, v86
	v_add_f32_e32 v84, 0, v84
	v_fmac_f32_e32 v81, v5, v83
	v_fmac_f32_e32 v79, v34, v88
	v_fmac_f32_e32 v85, v40, v80
	v_add_f32_e32 v80, v81, v84
	s_waitcnt lgkmcnt(0)
	v_mul_f32_e32 v81, v49, v95
	v_fmac_f32_e32 v79, v35, v89
	v_fmac_f32_e32 v85, v38, v82
	v_fmac_f32_e32 v81, v48, v94
	v_add_f32_e32 v79, 0, v79
	v_fmac_f32_e32 v85, v39, v83
	v_fmac_f32_e32 v81, v46, v96
	v_add_f32_e32 v79, v85, v79
	v_fmac_f32_e32 v81, v47, v97
	v_add_f32_e32 v79, v81, v79
	v_mul_f32_e32 v81, v45, v95
	v_fmac_f32_e32 v81, v44, v94
	v_fmac_f32_e32 v81, v42, v96
	v_fmac_f32_e32 v81, v43, v97
	v_add_f32_e32 v80, v81, v80
	v_mul_f32_e32 v81, v57, v91
	v_fmac_f32_e32 v81, v56, v90
	v_fmac_f32_e32 v81, v54, v92
	v_fmac_f32_e32 v81, v55, v93
	v_add_f32_e32 v79, v81, v79
	v_mul_f32_e32 v81, v53, v91
	v_fmac_f32_e32 v81, v52, v90
	v_fmac_f32_e32 v81, v50, v92
	v_fmac_f32_e32 v81, v51, v93
	v_add_f32_e32 v80, v81, v80
	ds_read_b128 v[82:85], v68 offset:40960
	ds_read_b128 v[86:89], v68 offset:41984
	s_waitcnt lgkmcnt(1)
	v_mul_f32_e32 v81, v37, v83
	v_mul_f32_e32 v83, v7, v83
	v_fmac_f32_e32 v81, v36, v82
	v_fmac_f32_e32 v83, v6, v82
	s_waitcnt lgkmcnt(0)
	v_mul_f32_e32 v82, v41, v87
	v_fmac_f32_e32 v81, v34, v84
	v_fmac_f32_e32 v82, v40, v86
	v_mul_f32_e32 v87, v9, v87
	v_fmac_f32_e32 v83, v2, v84
	v_fmac_f32_e32 v81, v35, v85
	v_fmac_f32_e32 v82, v38, v88
	v_fmac_f32_e32 v87, v8, v86
	v_add_f32_e32 v81, 0, v81
	v_fmac_f32_e32 v83, v3, v85
	v_fmac_f32_e32 v82, v39, v89
	v_fmac_f32_e32 v87, v4, v88
	v_add_f32_e32 v90, 0, v83
	v_add_f32_e32 v81, v81, v82
	ds_read_b128 v[82:85], v68 offset:43008
	v_fmac_f32_e32 v87, v5, v89
	v_add_f32_e32 v90, v90, v87
	ds_read_b128 v[86:89], v68 offset:44032
	s_waitcnt lgkmcnt(1)
	v_mul_f32_e32 v91, v49, v83
	v_mul_f32_e32 v83, v45, v83
	v_fmac_f32_e32 v91, v48, v82
	v_fmac_f32_e32 v83, v44, v82
	s_waitcnt lgkmcnt(0)
	v_mul_f32_e32 v82, v57, v87
	v_fmac_f32_e32 v91, v46, v84
	v_fmac_f32_e32 v82, v56, v86
	v_fmac_f32_e32 v91, v47, v85
	v_fmac_f32_e32 v83, v42, v84
	v_fmac_f32_e32 v82, v54, v88
	v_add_f32_e32 v81, v81, v91
	v_fmac_f32_e32 v83, v43, v85
	v_fmac_f32_e32 v82, v55, v89
	v_add_f32_e32 v94, v90, v83
	v_add_f32_e32 v81, v81, v82
	ds_read_b128 v[82:85], v68 offset:46080
	ds_read_b128 v[90:93], v68 offset:45056
	v_mul_f32_e32 v87, v53, v87
	v_fmac_f32_e32 v87, v52, v86
	v_fmac_f32_e32 v87, v50, v88
	v_fmac_f32_e32 v87, v51, v89
	s_waitcnt lgkmcnt(0)
	v_mul_f32_e32 v99, v37, v91
	v_mul_f32_e32 v91, v7, v91
	v_add_f32_e32 v98, v94, v87
	ds_read_b128 v[86:89], v68 offset:48128
	ds_read_b128 v[94:97], v68 offset:47104
	v_fmac_f32_e32 v91, v6, v90
	v_fmac_f32_e32 v91, v2, v92
	v_fmac_f32_e32 v91, v3, v93
	v_fmac_f32_e32 v99, v36, v90
	v_add_f32_e32 v90, 0, v91
	v_mul_f32_e32 v91, v41, v83
	v_mul_f32_e32 v83, v9, v83
	v_fmac_f32_e32 v91, v40, v82
	v_fmac_f32_e32 v83, v8, v82
	v_fmac_f32_e32 v91, v38, v84
	v_fmac_f32_e32 v83, v4, v84
	s_waitcnt lgkmcnt(0)
	v_mul_f32_e32 v84, v45, v95
	v_fmac_f32_e32 v84, v44, v94
	v_fmac_f32_e32 v83, v5, v85
	v_fmac_f32_e32 v84, v42, v96
	v_fmac_f32_e32 v99, v34, v92
	v_add_f32_e32 v82, v83, v90
	v_mul_f32_e32 v83, v49, v95
	v_fmac_f32_e32 v84, v43, v97
	v_fmac_f32_e32 v99, v35, v93
	v_fmac_f32_e32 v83, v48, v94
	v_add_f32_e32 v82, v84, v82
	v_mul_f32_e32 v84, v57, v87
	v_add_f32_e32 v99, 0, v99
	v_fmac_f32_e32 v91, v39, v85
	v_fmac_f32_e32 v83, v46, v96
	v_fmac_f32_e32 v84, v56, v86
	v_add_f32_e32 v91, v91, v99
	v_fmac_f32_e32 v83, v47, v97
	v_fmac_f32_e32 v84, v54, v88
	v_add_f32_e32 v83, v83, v91
	v_fmac_f32_e32 v84, v55, v89
	v_add_f32_e32 v99, v84, v83
	v_mul_f32_e32 v83, v53, v87
	v_fmac_f32_e32 v83, v52, v86
	v_fmac_f32_e32 v83, v50, v88
	v_fmac_f32_e32 v83, v51, v89
	v_add_f32_e32 v100, v83, v82
	ds_read_b128 v[82:85], v68 offset:49152
	ds_read_b128 v[86:89], v68 offset:50176
	s_waitcnt lgkmcnt(1)
	v_mul_f32_e32 v90, v37, v83
	v_mul_f32_e32 v83, v7, v83
	v_fmac_f32_e32 v90, v36, v82
	v_fmac_f32_e32 v83, v6, v82
	v_fmac_f32_e32 v90, v34, v84
	v_fmac_f32_e32 v83, v2, v84
	v_fmac_f32_e32 v90, v35, v85
	v_fmac_f32_e32 v83, v3, v85
	v_add_f32_e32 v82, 0, v90
	v_add_f32_e32 v90, 0, v83
	s_waitcnt lgkmcnt(0)
	v_mul_f32_e32 v83, v41, v87
	v_fmac_f32_e32 v83, v40, v86
	v_mul_f32_e32 v87, v9, v87
	v_fmac_f32_e32 v83, v38, v88
	v_fmac_f32_e32 v87, v8, v86
	v_fmac_f32_e32 v83, v39, v89
	v_fmac_f32_e32 v87, v4, v88
	v_add_f32_e32 v91, v82, v83
	ds_read_b128 v[82:85], v68 offset:51200
	v_fmac_f32_e32 v87, v5, v89
	v_add_f32_e32 v90, v90, v87
	ds_read_b128 v[86:89], v68 offset:52224
	s_waitcnt lgkmcnt(1)
	v_mul_f32_e32 v92, v49, v83
	v_mul_f32_e32 v83, v45, v83
	v_fmac_f32_e32 v92, v48, v82
	v_fmac_f32_e32 v83, v44, v82
	s_waitcnt lgkmcnt(0)
	v_mul_f32_e32 v82, v57, v87
	v_fmac_f32_e32 v92, v46, v84
	v_fmac_f32_e32 v82, v56, v86
	v_fmac_f32_e32 v92, v47, v85
	v_fmac_f32_e32 v83, v42, v84
	v_fmac_f32_e32 v82, v54, v88
	v_add_f32_e32 v91, v91, v92
	v_fmac_f32_e32 v83, v43, v85
	v_fmac_f32_e32 v82, v55, v89
	v_add_f32_e32 v94, v90, v83
	v_add_f32_e32 v101, v91, v82
	ds_read_b128 v[82:85], v68 offset:54272
	ds_read_b128 v[90:93], v68 offset:53248
	v_mul_f32_e32 v87, v53, v87
	v_fmac_f32_e32 v87, v52, v86
	v_fmac_f32_e32 v87, v50, v88
	v_fmac_f32_e32 v87, v51, v89
	s_waitcnt lgkmcnt(0)
	v_mul_f32_e32 v103, v37, v91
	v_mul_f32_e32 v91, v7, v91
	v_add_f32_e32 v102, v94, v87
	ds_read_b128 v[86:89], v68 offset:56320
	ds_read_b128 v[94:97], v68 offset:55296
	v_fmac_f32_e32 v91, v6, v90
	v_fmac_f32_e32 v91, v2, v92
	v_fmac_f32_e32 v91, v3, v93
	v_fmac_f32_e32 v103, v36, v90
	v_add_f32_e32 v90, 0, v91
	v_mul_f32_e32 v91, v41, v83
	v_mul_f32_e32 v83, v9, v83
	v_fmac_f32_e32 v91, v40, v82
	v_fmac_f32_e32 v83, v8, v82
	v_fmac_f32_e32 v91, v38, v84
	v_fmac_f32_e32 v83, v4, v84
	s_waitcnt lgkmcnt(0)
	v_mul_f32_e32 v84, v45, v95
	v_fmac_f32_e32 v84, v44, v94
	v_fmac_f32_e32 v83, v5, v85
	v_fmac_f32_e32 v84, v42, v96
	v_fmac_f32_e32 v103, v34, v92
	v_add_f32_e32 v82, v83, v90
	v_mul_f32_e32 v83, v49, v95
	v_fmac_f32_e32 v84, v43, v97
	v_fmac_f32_e32 v103, v35, v93
	v_fmac_f32_e32 v83, v48, v94
	v_add_f32_e32 v82, v84, v82
	v_mul_f32_e32 v84, v57, v87
	v_add_f32_e32 v103, 0, v103
	v_fmac_f32_e32 v91, v39, v85
	v_fmac_f32_e32 v83, v46, v96
	v_fmac_f32_e32 v84, v56, v86
	v_add_f32_e32 v91, v91, v103
	v_fmac_f32_e32 v83, v47, v97
	v_fmac_f32_e32 v84, v54, v88
	v_add_f32_e32 v83, v83, v91
	v_fmac_f32_e32 v84, v55, v89
	v_add_f32_e32 v103, v84, v83
	v_mul_f32_e32 v83, v53, v87
	v_fmac_f32_e32 v83, v52, v86
	v_fmac_f32_e32 v83, v50, v88
	v_fmac_f32_e32 v83, v51, v89
	v_add_f32_e32 v104, v83, v82
	ds_read_b128 v[82:85], v68 offset:57344
	ds_read_b128 v[86:89], v68 offset:58368
	s_waitcnt lgkmcnt(1)
	v_mul_f32_e32 v90, v37, v83
	v_mul_f32_e32 v83, v7, v83
	v_fmac_f32_e32 v90, v36, v82
	v_fmac_f32_e32 v83, v6, v82
	v_fmac_f32_e32 v90, v34, v84
	v_fmac_f32_e32 v83, v2, v84
	v_fmac_f32_e32 v90, v35, v85
	v_fmac_f32_e32 v83, v3, v85
	v_add_f32_e32 v82, 0, v90
	v_add_f32_e32 v90, 0, v83
	s_waitcnt lgkmcnt(0)
	v_mul_f32_e32 v83, v41, v87
	v_fmac_f32_e32 v83, v40, v86
	v_mul_f32_e32 v87, v9, v87
	v_fmac_f32_e32 v83, v38, v88
	v_fmac_f32_e32 v87, v8, v86
	v_fmac_f32_e32 v83, v39, v89
	v_fmac_f32_e32 v87, v4, v88
	v_add_f32_e32 v91, v82, v83
	ds_read_b128 v[82:85], v68 offset:59392
	v_fmac_f32_e32 v87, v5, v89
	v_add_f32_e32 v90, v90, v87
	ds_read_b128 v[86:89], v68 offset:60416
	s_waitcnt lgkmcnt(1)
	v_mul_f32_e32 v92, v49, v83
	v_mul_f32_e32 v83, v45, v83
	v_fmac_f32_e32 v92, v48, v82
	v_fmac_f32_e32 v83, v44, v82
	s_waitcnt lgkmcnt(0)
	v_mul_f32_e32 v82, v57, v87
	v_fmac_f32_e32 v92, v46, v84
	v_fmac_f32_e32 v82, v56, v86
	v_fmac_f32_e32 v92, v47, v85
	v_fmac_f32_e32 v83, v42, v84
	v_fmac_f32_e32 v82, v54, v88
	v_add_f32_e32 v91, v91, v92
	v_fmac_f32_e32 v83, v43, v85
	v_fmac_f32_e32 v82, v55, v89
	v_add_f32_e32 v94, v90, v83
	v_add_f32_e32 v105, v91, v82
	v_mul_f32_e32 v87, v53, v87
	ds_read_b128 v[82:85], v68 offset:62464
	ds_read_b128 v[90:93], v68 offset:61440
	v_fmac_f32_e32 v87, v52, v86
	v_fmac_f32_e32 v87, v50, v88
	v_fmac_f32_e32 v87, v51, v89
	v_add_f32_e32 v106, v94, v87
	ds_read_b128 v[86:89], v68 offset:64512
	ds_read_b128 v[94:97], v68 offset:63488
	s_waitcnt lgkmcnt(2)
	v_mul_f32_e32 v7, v7, v91
	v_fmac_f32_e32 v7, v6, v90
	v_mul_f32_e32 v37, v37, v91
	v_fmac_f32_e32 v7, v2, v92
	v_mul_f32_e32 v6, v9, v83
	v_fmac_f32_e32 v37, v36, v90
	v_fmac_f32_e32 v7, v3, v93
	v_mul_f32_e32 v3, v41, v83
	v_fmac_f32_e32 v6, v8, v82
	v_fmac_f32_e32 v37, v34, v92
	v_fmac_f32_e32 v3, v40, v82
	v_fmac_f32_e32 v6, v4, v84
	s_waitcnt lgkmcnt(0)
	v_mul_f32_e32 v4, v49, v95
	v_fmac_f32_e32 v37, v35, v93
	v_fmac_f32_e32 v3, v38, v84
	v_fmac_f32_e32 v4, v48, v94
	v_add_f32_e32 v34, 0, v37
	v_fmac_f32_e32 v3, v39, v85
	v_fmac_f32_e32 v4, v46, v96
	v_add_f32_e32 v3, v3, v34
	v_fmac_f32_e32 v4, v47, v97
	v_add_f32_e32 v3, v4, v3
	v_mul_f32_e32 v4, v45, v95
	v_fmac_f32_e32 v4, v44, v94
	v_add_f32_e32 v2, 0, v7
	v_fmac_f32_e32 v6, v5, v85
	v_fmac_f32_e32 v4, v42, v96
	v_add_f32_e32 v2, v6, v2
	v_fmac_f32_e32 v4, v43, v97
	v_add_f32_e32 v2, v4, v2
	v_mul_f32_e32 v4, v57, v87
	v_fmac_f32_e32 v4, v56, v86
	v_fmac_f32_e32 v4, v54, v88
	v_fmac_f32_e32 v4, v55, v89
	v_add_f32_e32 v3, v4, v3
	v_mul_f32_e32 v4, v53, v87
	v_fmac_f32_e32 v4, v52, v86
	v_fmac_f32_e32 v4, v50, v88
	v_fmac_f32_e32 v4, v51, v89
	v_add_f32_e32 v2, v4, v2
	v_cndmask_b32_e64 v4, v12, v58, s[0:1]
	ds_bpermute_b32 v4, v1, v4
	v_cndmask_b32_e64 v5, v58, v12, s[0:1]
	v_cndmask_b32_e64 v7, v11, v33, s[0:1]
	ds_bpermute_b32 v7, v1, v7
	v_cndmask_b32_e64 v8, v61, v62, s[0:1]
	s_waitcnt lgkmcnt(1)
	v_add_f32_e32 v4, v5, v4
	v_cndmask_b32_e64 v5, v59, v60, s[0:1]
	ds_bpermute_b32 v5, v1, v5
	ds_bpermute_b32 v8, v1, v8
	v_cndmask_b32_e64 v9, v63, v70, s[0:1]
	v_cndmask_b32_e64 v6, v33, v11, s[0:1]
	ds_bpermute_b32 v9, v1, v9
	v_cndmask_b32_e64 v11, v71, v72, s[0:1]
	ds_bpermute_b32 v11, v1, v11
	v_cndmask_b32_e64 v12, v73, v74, s[0:1]
	s_waitcnt lgkmcnt(4)
	v_add_f32_e32 v6, v6, v7
	v_cndmask_b32_e64 v7, v60, v59, s[0:1]
	ds_bpermute_b32 v12, v1, v12
	v_cndmask_b32_e64 v33, v75, v76, s[0:1]
	s_waitcnt lgkmcnt(4)
	v_add_f32_e32 v5, v7, v5
	v_cndmask_b32_e64 v7, v62, v61, s[0:1]
	ds_bpermute_b32 v33, v1, v33
	v_cndmask_b32_e64 v34, v77, v78, s[0:1]
	s_waitcnt lgkmcnt(4)
	v_add_f32_e32 v7, v7, v8
	v_cndmask_b32_e64 v8, v70, v63, s[0:1]
	ds_bpermute_b32 v34, v1, v34
	v_cndmask_b32_e64 v35, v79, v80, s[0:1]
	s_waitcnt lgkmcnt(4)
	v_add_f32_e32 v8, v8, v9
	v_cndmask_b32_e64 v9, v72, v71, s[0:1]
	ds_bpermute_b32 v35, v1, v35
	s_waitcnt lgkmcnt(4)
	v_add_f32_e32 v9, v9, v11
	v_cndmask_b32_e64 v11, v74, v73, s[0:1]
	s_waitcnt lgkmcnt(3)
	v_add_f32_e32 v11, v11, v12
	v_cndmask_b32_e64 v12, v76, v75, s[0:1]
	s_waitcnt lgkmcnt(2)
	v_add_f32_e32 v12, v12, v33
	v_cndmask_b32_e64 v33, v78, v77, s[0:1]
	v_cndmask_b32_e64 v36, v81, v98, s[0:1]
	s_waitcnt lgkmcnt(1)
	v_add_f32_e32 v33, v33, v34
	v_cndmask_b32_e64 v34, v80, v79, s[0:1]
	ds_bpermute_b32 v36, v1, v36
	v_cndmask_b32_e64 v37, v99, v100, s[0:1]
	s_waitcnt lgkmcnt(1)
	v_add_f32_e32 v34, v34, v35
	ds_bpermute_b32 v37, v1, v37
	v_cndmask_b32_e64 v38, v101, v102, s[0:1]
	v_cndmask_b32_e64 v41, v3, v2, s[0:1]
	v_cndmask_b32_e64 v2, v2, v3, s[0:1]
	v_cndmask_b32_e64 v3, v33, v4, s[6:7]
	v_cndmask_b32_e64 v4, v4, v33, s[6:7]
	ds_bpermute_b32 v38, v1, v38
	ds_bpermute_b32 v4, v31, v4
	v_cndmask_b32_e64 v33, v6, v34, s[6:7]
	ds_bpermute_b32 v33, v31, v33
	v_cndmask_b32_e64 v35, v98, v81, s[0:1]
	s_waitcnt lgkmcnt(4)
	v_add_f32_e32 v35, v35, v36
	v_cndmask_b32_e64 v36, v100, v99, s[0:1]
	s_waitcnt lgkmcnt(3)
	v_add_f32_e32 v36, v36, v37
	v_cndmask_b32_e64 v37, v102, v101, s[0:1]
	v_cndmask_b32_e64 v39, v103, v104, s[0:1]
	s_waitcnt lgkmcnt(2)
	v_add_f32_e32 v37, v37, v38
	ds_bpermute_b32 v39, v1, v39
	v_cndmask_b32_e64 v40, v105, v106, s[0:1]
	s_waitcnt lgkmcnt(2)
	v_add_f32_e32 v3, v3, v4
	v_cndmask_b32_e64 v4, v34, v6, s[6:7]
	v_cndmask_b32_e64 v6, v36, v7, s[6:7]
	v_cndmask_b32_e64 v7, v7, v36, s[6:7]
	ds_bpermute_b32 v40, v1, v40
	ds_bpermute_b32 v41, v1, v41
	s_waitcnt lgkmcnt(3)
	v_add_f32_e32 v4, v4, v33
	ds_bpermute_b32 v7, v31, v7
	v_cndmask_b32_e64 v33, v8, v37, s[6:7]
	ds_bpermute_b32 v33, v31, v33
	v_cndmask_b32_e64 v38, v104, v103, s[0:1]
	s_waitcnt lgkmcnt(4)
	v_add_f32_e32 v38, v38, v39
	v_cndmask_b32_e64 v39, v106, v105, s[0:1]
	s_waitcnt lgkmcnt(3)
	v_add_f32_e32 v39, v39, v40
	s_waitcnt lgkmcnt(2)
	v_add_f32_e32 v2, v2, v41
	s_waitcnt lgkmcnt(1)
	v_add_f32_e32 v6, v6, v7
	v_cndmask_b32_e64 v7, v37, v8, s[6:7]
	v_cndmask_b32_e64 v40, v5, v35, s[6:7]
	v_cndmask_b32_e64 v34, v9, v38, s[6:7]
	s_waitcnt lgkmcnt(0)
	v_add_f32_e32 v7, v7, v33
	v_cndmask_b32_e64 v8, v38, v9, s[6:7]
	v_cndmask_b32_e64 v9, v39, v11, s[6:7]
	v_cndmask_b32_e64 v11, v11, v39, s[6:7]
	v_cndmask_b32_e64 v33, v12, v2, s[6:7]
	ds_bpermute_b32 v40, v31, v40
	ds_bpermute_b32 v34, v31, v34
	ds_bpermute_b32 v11, v31, v11
	ds_bpermute_b32 v33, v31, v33
	v_cndmask_b32_e64 v5, v35, v5, s[6:7]
	v_cndmask_b32_e64 v2, v2, v12, s[6:7]
	s_waitcnt lgkmcnt(3)
	v_add_f32_e32 v5, v5, v40
	s_waitcnt lgkmcnt(2)
	v_add_f32_e32 v8, v8, v34
	s_waitcnt lgkmcnt(1)
	v_add_f32_e32 v9, v9, v11
	s_waitcnt lgkmcnt(0)
	v_add_f32_e32 v2, v2, v33
	v_cndmask_b32_e64 v34, v3, v7, s[8:9]
	v_cndmask_b32_e64 v3, v7, v3, s[8:9]
	v_cndmask_b32_e64 v7, v8, v4, s[8:9]
	v_cndmask_b32_e64 v4, v4, v8, s[8:9]
	v_cndmask_b32_e64 v8, v5, v9, s[8:9]
	v_cndmask_b32_e64 v11, v6, v2, s[8:9]
	ds_bpermute_b32 v34, v64, v34
	ds_bpermute_b32 v4, v64, v4
	ds_bpermute_b32 v8, v64, v8
	ds_bpermute_b32 v11, v64, v11
	v_cndmask_b32_e64 v5, v9, v5, s[8:9]
	v_cndmask_b32_e64 v2, v2, v6, s[8:9]
	s_waitcnt lgkmcnt(3)
	v_add_f32_e32 v3, v3, v34
	s_waitcnt lgkmcnt(2)
	v_add_f32_e32 v4, v7, v4
	s_waitcnt lgkmcnt(1)
	v_add_f32_e32 v5, v5, v8
	s_waitcnt lgkmcnt(0)
	v_add_f32_e32 v2, v2, v11
	v_cndmask_b32_e64 v6, v3, v5, s[10:11]
	v_cndmask_b32_e64 v7, v4, v2, s[10:11]
	ds_bpermute_b32 v6, v65, v6
	ds_bpermute_b32 v7, v65, v7
	v_cndmask_b32_e64 v3, v5, v3, s[10:11]
	v_cndmask_b32_e64 v2, v2, v4, s[10:11]
	s_waitcnt lgkmcnt(1)
	v_add_f32_e32 v3, v3, v6
	s_waitcnt lgkmcnt(0)
	v_add_f32_e32 v2, v2, v7
	v_cndmask_b32_e64 v4, v3, v2, s[12:13]
	ds_bpermute_b32 v4, v66, v4
	v_cndmask_b32_e64 v2, v2, v3, s[12:13]
	s_waitcnt lgkmcnt(0)
	v_add_f32_e32 v2, v2, v4
	ds_bpermute_b32 v3, v67, v2
	s_waitcnt lgkmcnt(0)
	v_add_f32_e32 v2, v2, v3
	ds_bpermute_b32 v3, v66, v2
	s_waitcnt lgkmcnt(0)
	v_max_f32_e32 v3, v3, v3
	v_max_f32_e32 v3, v2, v3
	ds_bpermute_b32 v4, v65, v3
	s_waitcnt lgkmcnt(0)
	v_max_f32_e32 v4, v4, v4
	v_max_f32_e32 v3, v3, v4
	ds_bpermute_b32 v4, v64, v3
	s_waitcnt lgkmcnt(0)
	v_max_f32_e32 v4, v4, v4
	v_max_f32_e32 v3, v3, v4
	ds_bpermute_b32 v4, v31, v3
	s_waitcnt lgkmcnt(0)
	v_max_f32_e32 v4, v4, v4
	v_max_f32_e32 v3, v3, v4
	v_sub_f32_e32 v2, v2, v3
	v_mul_f32_e32 v2, 0x3fb8aa3b, v2
	v_exp_f32_e32 v2, v2
	ds_bpermute_b32 v3, v66, v2
	s_waitcnt lgkmcnt(0)
	v_add_f32_e32 v3, v2, v3
	ds_bpermute_b32 v4, v65, v3
	s_waitcnt lgkmcnt(0)
	v_add_f32_e32 v3, v3, v4
	ds_bpermute_b32 v4, v64, v3
	s_waitcnt lgkmcnt(0)
	v_add_f32_e32 v3, v3, v4
	ds_bpermute_b32 v4, v31, v3
	s_and_saveexec_b64 s[4:5], s[14:15]
	s_cbranch_execz .LBB0_640
	s_waitcnt lgkmcnt(0)
	v_add_f32_e32 v3, v3, v4
	v_div_scale_f32 v4, s[28:29], v3, v3, v2
	v_rcp_f32_e32 v5, v4
	v_ashrrev_i32_e32 v33, 31, v32
	v_and_or_b32 v6, v10, s25, v69
	v_lshlrev_b32_e32 v12, 2, v6
	v_fma_f32 v7, -v4, v5, 1.0
	v_fmac_f32_e32 v5, v7, v5
	v_div_scale_f32 v7, vcc, v2, v3, v2
	v_mul_f32_e32 v8, v7, v5
	v_fma_f32 v9, -v4, v8, v7
	v_fmac_f32_e32 v8, v9, v5
	v_fma_f32 v4, -v4, v8, v7
	v_div_fmas_f32 v4, v4, v5, v8
	v_div_fixup_f32 v4, v4, v3, v2
	v_lshlrev_b64 v[2:3], 18, v[32:33]
	v_lshl_add_u64 v[2:3], v[18:19], 0, v[2:3]
	v_lshl_add_u64 v[2:3], v[2:3], 0, v[12:13]
	global_store_dword v[2:3], v4, off
	s_branch .LBB0_640

.LBB0_1230:
	v_ashrrev_i32_e32 v11, 31, v10
	v_lshlrev_b64 v[44:45], 11, v[10:11]
	v_lshl_add_u64 v[2:3], v[14:15], 0, v[44:45]
	global_load_dwordx2 v[46:47], v[2:3], off
	global_load_dwordx2 v[50:51], v[2:3], off offset:512
	global_load_dwordx2 v[52:53], v[2:3], off offset:1024
	global_load_dwordx2 v[54:55], v[2:3], off offset:1536
	s_waitcnt lgkmcnt(0)
	v_add_u32_e32 v4, 1, v10
	v_ashrrev_i32_e32 v5, 31, v4
	v_lshlrev_b64 v[66:67], 11, v[4:5]
	v_lshl_add_u64 v[2:3], v[14:15], 0, v[66:67]
	global_load_dwordx2 v[62:63], v[2:3], off
	global_load_dwordx2 v[64:65], v[2:3], off offset:512
	global_load_dwordx2 v[68:69], v[2:3], off offset:1024
	global_load_dwordx2 v[76:77], v[2:3], off offset:1536
	v_ashrrev_i32_e32 v38, 12, v10
	v_mul_hi_i32_i24_e32 v7, 0x6000, v38
	v_mul_i32_i24_e32 v6, 0x6000, v38
	v_lshl_add_u64 v[6:7], s[44:45], 0, v[6:7]
	v_lshl_add_u64 v[60:61], v[6:7], 0, s[20:21]
	v_lshl_add_u64 v[48:49], v[6:7], 0, s[22:23]
	v_lshl_add_u64 v[6:7], v[60:61], 0, v[28:29]
	v_lshl_add_u64 v[40:41], v[48:49], 0, v[28:29]
	global_load_dwordx4 v[200:203], v[18:19], off
	v_lshl_add_u64 v[236:237], v[48:49], 0, v[30:31]
	global_load_dwordx4 v[204:207], v[236:237], off
	v_lshl_add_u64 v[236:237], v[60:61], 0, v[30:31]
	global_load_dwordx4 v[208:211], v[236:237], off
	global_load_dwordx4 v[212:215], v[20:21], off
	v_lshl_add_u64 v[236:237], v[48:49], 0, v[32:33]
	global_load_dwordx4 v[216:219], v[236:237], off
	v_lshl_add_u64 v[236:237], v[60:61], 0, v[32:33]
	global_load_dwordx4 v[220:223], v[236:237], off
	global_load_dwordx4 v[224:227], v[22:23], off
	v_lshl_add_u64 v[236:237], v[48:49], 0, v[34:35]
	global_load_dwordx4 v[228:231], v[236:237], off
	v_lshl_add_u64 v[236:237], v[60:61], 0, v[34:35]
	global_load_dwordx4 v[232:235], v[236:237], off
	global_load_dwordx4 v[2:5], v[16:17], off
	s_nop 0
	global_load_dwordx4 v[6:9], v[6:7], off
	s_nop 0
	global_load_dwordx4 v[40:43], v[40:41], off
	v_lshl_add_u64 v[66:67], v[26:27], 0, v[66:67]
	s_waitcnt vmcnt(19)
	v_and_b32_e32 v81, 0xffff0000, v46
	s_waitcnt vmcnt(18)
	v_and_b32_e32 v85, 0xffff0000, v50
	s_waitcnt vmcnt(17)
	v_and_b32_e32 v89, 0xffff0000, v52
	s_waitcnt vmcnt(16)
	v_and_b32_e32 v59, 0xffff0000, v54
	v_lshlrev_b32_e32 v88, 16, v52
	v_lshlrev_b32_e32 v58, 16, v54
	v_mov_b32_e32 v102, v89
	v_mov_b32_e32 v103, v59
	v_lshlrev_b32_e32 v86, 16, v53
	v_lshlrev_b32_e32 v56, 16, v55
	v_mov_b32_e32 v100, v88
	v_mov_b32_e32 v101, v58
	v_pk_mul_f32 v[102:103], v[102:103], v[102:103]
	v_lshlrev_b32_e32 v80, 16, v46
	v_lshlrev_b32_e32 v82, 16, v51
	v_and_b32_e32 v83, 0xffff0000, v51
	v_lshlrev_b32_e32 v84, 16, v50
	v_and_b32_e32 v87, 0xffff0000, v53
	v_and_b32_e32 v57, 0xffff0000, v55
	s_waitcnt vmcnt(15)
	v_and_b32_e32 v51, 0xffff0000, v62
	v_mov_b32_e32 v90, v81
	v_mov_b32_e32 v91, v85
	s_waitcnt vmcnt(14)
	v_lshlrev_b32_e32 v92, 16, v65
	v_and_b32_e32 v93, 0xffff0000, v65
	v_lshlrev_b32_e32 v94, 16, v64
	v_and_b32_e32 v95, 0xffff0000, v64
	v_mov_b32_e32 v64, v86
	v_mov_b32_e32 v65, v56
	v_pk_fma_f32 v[100:101], v[100:101], v[100:101], v[102:103]
	v_lshlrev_b32_e32 v78, 16, v47
	v_and_b32_e32 v79, 0xffff0000, v47
	v_lshlrev_b32_e32 v46, 16, v63
	v_and_b32_e32 v47, 0xffff0000, v63
	v_lshlrev_b32_e32 v50, 16, v62
	v_mov_b32_e32 v62, v80
	v_mov_b32_e32 v63, v84
	s_waitcnt vmcnt(13)
	v_lshlrev_b32_e32 v96, 16, v69
	v_and_b32_e32 v97, 0xffff0000, v69
	v_lshlrev_b32_e32 v98, 16, v68
	v_and_b32_e32 v99, 0xffff0000, v68
	v_mov_b32_e32 v68, v87
	v_mov_b32_e32 v69, v57
	v_pk_mul_f32 v[90:91], v[90:91], v[90:91]
	v_mov_b32_e32 v110, v51
	v_mov_b32_e32 v111, v95
	v_pk_fma_f32 v[64:65], v[64:65], v[64:65], v[100:101]
	v_mov_b32_e32 v52, v78
	v_mov_b32_e32 v53, v82
	v_mov_b32_e32 v108, v50
	v_mov_b32_e32 v109, v94
	v_pk_fma_f32 v[62:63], v[62:63], v[62:63], v[90:91]
	v_pk_mul_f32 v[90:91], v[110:111], v[110:111]
	v_pk_fma_f32 v[64:65], v[68:69], v[68:69], v[64:65]
	s_waitcnt vmcnt(12)
	v_and_b32_e32 v69, 0xffff0000, v76
	v_mov_b32_e32 v54, v79
	v_mov_b32_e32 v55, v83
	v_mov_b32_e32 v104, v46
	v_mov_b32_e32 v105, v92
	v_pk_fma_f32 v[52:53], v[52:53], v[52:53], v[62:63]
	v_pk_fma_f32 v[62:63], v[108:109], v[108:109], v[90:91]
	v_lshlrev_b32_e32 v68, 16, v76
	v_mov_b32_e32 v102, v99
	v_mov_b32_e32 v103, v69
	v_pk_fma_f32 v[52:53], v[54:55], v[54:55], v[52:53]
	v_pk_fma_f32 v[54:55], v[104:105], v[104:105], v[62:63]
	v_lshlrev_b32_e32 v62, 16, v77
	v_mov_b32_e32 v100, v98
	v_mov_b32_e32 v101, v68
	v_pk_mul_f32 v[102:103], v[102:103], v[102:103]
	v_mov_b32_e32 v106, v47
	v_mov_b32_e32 v107, v93
	v_and_b32_e32 v63, 0xffff0000, v77
	v_mov_b32_e32 v76, v96
	v_mov_b32_e32 v77, v62
	v_pk_fma_f32 v[100:101], v[100:101], v[100:101], v[102:103]
	v_pk_fma_f32 v[54:55], v[106:107], v[106:107], v[54:55]
	v_mov_b32_e32 v90, v97
	v_mov_b32_e32 v91, v63
	v_pk_fma_f32 v[76:77], v[76:77], v[76:77], v[100:101]
	s_nop 0
	v_pk_fma_f32 v[76:77], v[90:91], v[90:91], v[76:77]
	v_mov_b32_e32 v90, v54
	v_mov_b32_e32 v91, v52
	v_mov_b32_e32 v52, v55
	v_pk_add_f32 v[52:53], v[90:91], v[52:53]
	v_mov_b32_e32 v54, v76
	v_mov_b32_e32 v55, v64
	v_pk_add_f32 v[52:53], v[52:53], v[54:55]
	v_mov_b32_e32 v64, v77
	v_pk_add_f32 v[52:53], v[52:53], v[64:65]
	ds_bpermute_b32 v55, v1, v53
	ds_bpermute_b32 v54, v1, v52
	s_waitcnt vmcnt(0)
	v_pk_add_f32 v[76:77], v[40:41], 1.0 op_sel_hi:[1,0]
	v_pk_add_f32 v[90:91], v[42:43], 1.0 op_sel_hi:[1,0]
	v_lshl_add_u64 v[64:65], v[26:27], 0, v[44:45]
	s_waitcnt lgkmcnt(0)
	v_pk_add_f32 v[52:53], v[52:53], v[54:55]
	ds_bpermute_b32 v55, v37, v53
	ds_bpermute_b32 v54, v37, v52
	s_waitcnt lgkmcnt(0)
	v_pk_add_f32 v[52:53], v[52:53], v[54:55]
	ds_bpermute_b32 v55, v70, v53
	ds_bpermute_b32 v54, v70, v52
	s_waitcnt lgkmcnt(0)
	v_pk_add_f32 v[52:53], v[52:53], v[54:55]
	ds_bpermute_b32 v55, v71, v53
	ds_bpermute_b32 v54, v71, v52
	s_waitcnt lgkmcnt(0)
	v_pk_add_f32 v[52:53], v[52:53], v[54:55]
	ds_bpermute_b32 v55, v72, v53
	ds_bpermute_b32 v54, v72, v52
	s_waitcnt lgkmcnt(0)
	v_pk_add_f32 v[52:53], v[52:53], v[54:55]
	ds_bpermute_b32 v55, v73, v53
	ds_bpermute_b32 v54, v73, v52
	s_waitcnt lgkmcnt(0)
	v_pk_add_f32 v[40:41], v[52:53], v[54:55]
	s_nop 0
	v_pk_fma_f32 v[52:53], v[40:41], s[24:25], v[36:37] op_sel_hi:[1,0,0]
	v_lshl_add_u64 v[54:55], v[48:49], 0, v[30:31]
	v_mul_f32_e32 v11, 0x4b800000, v53
	v_cmp_gt_f32_e32 vcc, s26, v53
	s_nop 1
	v_cndmask_b32_e32 v11, v53, v11, vcc
	v_rsq_f32_e32 v11, v11
	s_nop 0
	v_mul_f32_e32 v12, 0x45800000, v11
	v_cndmask_b32_e32 v12, v11, v12, vcc
	v_mul_f32_e32 v11, 0x4b800000, v52
	v_cmp_gt_f32_e32 vcc, s26, v52
	v_pk_mul_f32 v[40:41], v[12:13], v[80:81] op_sel_hi:[0,1]
	v_pk_mul_f32 v[40:41], v[2:3], v[40:41]
	v_cndmask_b32_e32 v11, v52, v11, vcc
	v_rsq_f32_e32 v11, v11
	v_pk_fma_f32 v[42:43], v[76:77], v[40:41], v[6:7]
	v_pk_mul_f32 v[40:41], v[12:13], v[78:79] op_sel_hi:[0,1]
	v_pk_mul_f32 v[40:41], v[4:5], v[40:41]
	v_mul_f32_e32 v39, 0x45800000, v11
	v_pk_fma_f32 v[40:41], v[90:91], v[40:41], v[8:9]
	v_cvt_pk_bf16_f32 v44, v42, v43
	v_cvt_pk_bf16_f32 v45, v40, v41
	v_cndmask_b32_e32 v120, v11, v39, vcc
	global_store_dwordx2 v[64:65], v[44:45], off
	v_pk_mul_f32 v[44:45], v[120:121], v[50:51] op_sel_hi:[0,1]
	v_pk_mul_f32 v[2:3], v[2:3], v[44:45]
	v_pk_mul_f32 v[80:81], v[120:121], v[94:95] op_sel_hi:[0,1]
	v_pk_fma_f32 v[6:7], v[76:77], v[2:3], v[6:7]
	v_pk_mul_f32 v[2:3], v[120:121], v[46:47] op_sel_hi:[0,1]
	v_pk_mul_f32 v[2:3], v[4:5], v[2:3]
	v_cvt_pk_bf16_f32 v4, v6, v7
	v_pk_fma_f32 v[2:3], v[90:91], v[2:3], v[8:9]
	v_pk_mul_f32 v[8:9], v[12:13], v[82:83] op_sel_hi:[0,1]
	v_cvt_pk_bf16_f32 v5, v2, v3
	global_store_dwordx2 v[66:67], v[4:5], off
	v_mov_b32_e32 v44, v200
	v_mov_b32_e32 v45, v201
	v_mov_b32_e32 v46, v202
	v_mov_b32_e32 v47, v203
	v_mov_b32_e32 v50, v204
	v_mov_b32_e32 v51, v205
	v_mov_b32_e32 v52, v206
	v_mov_b32_e32 v53, v207
	v_lshl_add_u64 v[4:5], v[60:61], 0, v[30:31]
	v_mov_b32_e32 v76, v208
	v_mov_b32_e32 v77, v209
	v_mov_b32_e32 v78, v210
	v_mov_b32_e32 v79, v211
	v_pk_mul_f32 v[4:5], v[12:13], v[84:85] op_sel_hi:[0,1]
	v_pk_mul_f32 v[82:83], v[120:121], v[92:93] op_sel_hi:[0,1]
	v_lshl_add_u64 v[54:55], v[48:49], 0, v[32:33]
	v_lshl_add_u64 v[84:85], v[48:49], 0, v[34:35]
	v_pk_mul_f32 v[48:49], v[12:13], v[88:89] op_sel_hi:[0,1]
	v_pk_mul_f32 v[88:89], v[120:121], v[96:97] op_sel_hi:[0,1]
	v_pk_mul_f32 v[58:59], v[12:13], v[58:59] op_sel_hi:[0,1]
	v_pk_mul_f32 v[56:57], v[12:13], v[56:57] op_sel_hi:[0,1]
	v_pk_mul_f32 v[62:63], v[120:121], v[62:63] op_sel_hi:[0,1]
	v_pk_mul_f32 v[4:5], v[44:45], v[4:5]
	v_pk_add_f32 v[50:51], v[50:51], 1.0 op_sel_hi:[1,0]
	v_pk_mul_f32 v[8:9], v[46:47], v[8:9]
	v_pk_add_f32 v[52:53], v[52:53], 1.0 op_sel_hi:[1,0]
	v_pk_mul_f32 v[80:81], v[44:45], v[80:81]
	v_pk_mul_f32 v[82:83], v[46:47], v[82:83]
	v_pk_fma_f32 v[46:47], v[4:5], v[50:51], v[76:77]
	v_pk_fma_f32 v[44:45], v[8:9], v[52:53], v[78:79]
	v_pk_fma_f32 v[8:9], v[50:51], v[80:81], v[76:77]
	v_pk_fma_f32 v[4:5], v[52:53], v[82:83], v[78:79]
	v_cvt_pk_bf16_f32 v50, v46, v47
	v_cvt_pk_bf16_f32 v51, v44, v45
	v_cvt_pk_bf16_f32 v52, v8, v9
	v_cvt_pk_bf16_f32 v53, v4, v5
	global_store_dwordx2 v[64:65], v[50:51], off offset:512
	global_store_dwordx2 v[66:67], v[52:53], off offset:512
	v_mov_b32_e32 v50, v212
	v_mov_b32_e32 v51, v213
	v_mov_b32_e32 v52, v214
	v_mov_b32_e32 v53, v215
	s_nop 0
	v_mov_b32_e32 v76, v216
	v_mov_b32_e32 v77, v217
	v_mov_b32_e32 v78, v218
	v_mov_b32_e32 v79, v219
	v_lshl_add_u64 v[54:55], v[60:61], 0, v[32:33]
	v_mov_b32_e32 v80, v220
	v_mov_b32_e32 v81, v221
	v_mov_b32_e32 v82, v222
	v_mov_b32_e32 v83, v223
	v_pk_mul_f32 v[54:55], v[12:13], v[86:87] op_sel_hi:[0,1]
	v_pk_mul_f32 v[86:87], v[120:121], v[98:99] op_sel_hi:[0,1]
	v_lshl_add_u64 v[60:61], v[60:61], 0, v[34:35]
	v_pk_mul_f32 v[48:49], v[48:49], v[50:51]
	v_pk_add_f32 v[76:77], v[76:77], 1.0 op_sel_hi:[1,0]
	v_pk_mul_f32 v[90:91], v[54:55], v[52:53]
	v_pk_add_f32 v[78:79], v[78:79], 1.0 op_sel_hi:[1,0]
	v_pk_mul_f32 v[50:51], v[86:87], v[50:51]
	v_pk_mul_f32 v[86:87], v[88:89], v[52:53]
	v_pk_fma_f32 v[54:55], v[48:49], v[76:77], v[80:81]
	v_pk_fma_f32 v[52:53], v[90:91], v[78:79], v[82:83]
	v_pk_fma_f32 v[50:51], v[50:51], v[76:77], v[80:81]
	v_pk_fma_f32 v[48:49], v[86:87], v[78:79], v[82:83]
	v_cvt_pk_bf16_f32 v76, v54, v55
	v_cvt_pk_bf16_f32 v77, v52, v53
	v_cvt_pk_bf16_f32 v78, v50, v51
	v_cvt_pk_bf16_f32 v79, v48, v49
	global_store_dwordx2 v[64:65], v[76:77], off offset:1024
	global_store_dwordx2 v[66:67], v[78:79], off offset:1024
	v_mov_b32_e32 v76, v224
	v_mov_b32_e32 v77, v225
	v_mov_b32_e32 v78, v226
	v_mov_b32_e32 v79, v227
	s_nop 0
	v_mov_b32_e32 v80, v228
	v_mov_b32_e32 v81, v229
	v_mov_b32_e32 v82, v230
	v_mov_b32_e32 v83, v231
	v_pk_mul_f32 v[58:59], v[58:59], v[76:77]
	v_mov_b32_e32 v84, v232
	v_mov_b32_e32 v85, v233
	v_mov_b32_e32 v86, v234
	v_mov_b32_e32 v87, v235
	ds_read_b128 v[88:91], v74
	ds_read_b128 v[92:95], v74 offset:1024
	ds_read_b128 v[96:99], v74 offset:2048
	ds_read_b128 v[100:103], v74 offset:3072
	ds_read_b128 v[104:107], v74 offset:7168
	ds_read_b128 v[108:111], v74 offset:6144
	ds_read_b128 v[112:115], v74 offset:5120
	ds_read_b128 v[116:119], v74 offset:4096
	s_waitcnt lgkmcnt(7)
	v_mul_f32_e32 v11, v43, v89
	v_mul_f32_e32 v12, v7, v89
	v_pk_mul_f32 v[60:61], v[120:121], v[68:69] op_sel_hi:[0,1]
	v_fmac_f32_e32 v11, v42, v88
	s_waitcnt lgkmcnt(0)
	v_mul_f32_e32 v39, v43, v117
	v_mul_f32_e32 v68, v7, v117
	v_fmac_f32_e32 v12, v6, v88
	v_fmac_f32_e32 v39, v42, v116
	v_fmac_f32_e32 v68, v6, v116
	v_fmac_f32_e32 v11, v40, v90
	v_fmac_f32_e32 v12, v2, v90
	v_mul_f32_e32 v69, v47, v93
	v_mul_f32_e32 v89, v47, v113
	v_mul_f32_e32 v90, v9, v113
	v_fmac_f32_e32 v39, v40, v118
	v_fmac_f32_e32 v68, v2, v118
	v_fmac_f32_e32 v69, v46, v92
	v_fmac_f32_e32 v89, v46, v112
	v_fmac_f32_e32 v90, v8, v112
	v_fmac_f32_e32 v11, v41, v91
	v_fmac_f32_e32 v39, v41, v119
	v_fmac_f32_e32 v68, v3, v119
	v_mul_f32_e32 v88, v9, v93
	v_fmac_f32_e32 v69, v44, v94
	v_fmac_f32_e32 v89, v44, v114
	v_fmac_f32_e32 v90, v4, v114
	v_add_f32_e32 v11, 0, v11
	v_add_f32_e32 v39, 0, v39
	v_add_f32_e32 v68, 0, v68
	v_fmac_f32_e32 v88, v8, v92
	v_fmac_f32_e32 v69, v45, v95
	v_fmac_f32_e32 v89, v45, v115
	v_fmac_f32_e32 v90, v5, v115
	v_fmac_f32_e32 v12, v3, v91
	v_fmac_f32_e32 v88, v4, v94
	v_add_f32_e32 v11, v11, v69
	v_add_f32_e32 v39, v89, v39
	v_add_f32_e32 v68, v90, v68
	v_mul_f32_e32 v69, v55, v97
	v_mul_f32_e32 v89, v55, v109
	v_mul_f32_e32 v90, v51, v109
	v_add_f32_e32 v12, 0, v12
	v_fmac_f32_e32 v88, v5, v95
	v_fmac_f32_e32 v69, v54, v96
	v_fmac_f32_e32 v89, v54, v108
	v_fmac_f32_e32 v90, v50, v108
	v_add_f32_e32 v12, v12, v88
	v_mul_f32_e32 v88, v51, v97
	v_fmac_f32_e32 v69, v52, v98
	v_fmac_f32_e32 v89, v52, v110
	v_fmac_f32_e32 v90, v48, v110
	v_fmac_f32_e32 v88, v50, v96
	v_fmac_f32_e32 v69, v53, v99
	v_fmac_f32_e32 v89, v53, v111
	v_fmac_f32_e32 v90, v49, v111
	v_fmac_f32_e32 v88, v48, v98
	v_add_f32_e32 v11, v11, v69
	v_add_f32_e32 v39, v89, v39
	v_add_f32_e32 v89, v90, v68
	v_pk_add_f32 v[68:69], v[80:81], 1.0 op_sel_hi:[1,0]
	v_pk_mul_f32 v[76:77], v[60:61], v[76:77]
	v_fmac_f32_e32 v88, v49, v99
	v_pk_mul_f32 v[56:57], v[56:57], v[78:79]
	v_pk_add_f32 v[80:81], v[82:83], 1.0 op_sel_hi:[1,0]
	v_pk_mul_f32 v[78:79], v[62:63], v[78:79]
	v_add_f32_e32 v88, v12, v88
	v_pk_fma_f32 v[62:63], v[58:59], v[68:69], v[84:85]
	v_pk_fma_f32 v[58:59], v[76:77], v[68:69], v[84:85]
	v_pk_fma_f32 v[60:61], v[56:57], v[80:81], v[86:87]
	v_pk_fma_f32 v[56:57], v[78:79], v[80:81], v[86:87]
	v_mul_f32_e32 v12, v63, v101
	v_mul_f32_e32 v78, v59, v101
	v_mul_f32_e32 v79, v63, v105
	v_mul_f32_e32 v80, v59, v105
	v_fmac_f32_e32 v12, v62, v100
	v_fmac_f32_e32 v78, v58, v100
	v_fmac_f32_e32 v79, v62, v104
	v_fmac_f32_e32 v80, v58, v104
	v_fmac_f32_e32 v12, v60, v102
	v_fmac_f32_e32 v78, v56, v102
	v_fmac_f32_e32 v79, v60, v106
	v_fmac_f32_e32 v80, v56, v106
	v_cvt_pk_bf16_f32 v68, v62, v63
	v_cvt_pk_bf16_f32 v69, v60, v61
	v_fmac_f32_e32 v12, v61, v103
	v_fmac_f32_e32 v78, v57, v103
	v_fmac_f32_e32 v79, v61, v107
	v_fmac_f32_e32 v80, v57, v107
	v_cvt_pk_bf16_f32 v76, v58, v59
	v_cvt_pk_bf16_f32 v77, v56, v57
	global_store_dwordx2 v[64:65], v[68:69], off offset:1536
	global_store_dwordx2 v[66:67], v[76:77], off offset:1536
	v_add_f32_e32 v12, v11, v12
	v_add_f32_e32 v64, v88, v78
	v_add_f32_e32 v11, v79, v39
	v_add_f32_e32 v39, v80, v89
	ds_read_b128 v[66:69], v74 offset:8192
	ds_read_b128 v[76:79], v74 offset:9216
	s_waitcnt lgkmcnt(1)
	v_mul_f32_e32 v65, v43, v67
	v_mul_f32_e32 v67, v7, v67
	v_fmac_f32_e32 v65, v42, v66
	v_fmac_f32_e32 v67, v6, v66
	s_waitcnt lgkmcnt(0)
	v_mul_f32_e32 v66, v47, v77
	v_fmac_f32_e32 v65, v40, v68
	v_fmac_f32_e32 v66, v46, v76
	v_fmac_f32_e32 v67, v2, v68
	v_fmac_f32_e32 v65, v41, v69
	v_fmac_f32_e32 v66, v44, v78
	v_add_f32_e32 v65, 0, v65
	v_fmac_f32_e32 v67, v3, v69
	v_fmac_f32_e32 v66, v45, v79
	v_add_f32_e32 v80, 0, v67
	v_add_f32_e32 v65, v65, v66
	v_mul_f32_e32 v77, v9, v77
	ds_read_b128 v[66:69], v74 offset:10240
	v_fmac_f32_e32 v77, v8, v76
	v_fmac_f32_e32 v77, v4, v78
	v_fmac_f32_e32 v77, v5, v79
	v_add_f32_e32 v80, v80, v77
	ds_read_b128 v[76:79], v74 offset:11264
	s_waitcnt lgkmcnt(1)
	v_mul_f32_e32 v81, v55, v67
	v_mul_f32_e32 v67, v51, v67
	v_fmac_f32_e32 v67, v50, v66
	v_fmac_f32_e32 v67, v48, v68
	v_fmac_f32_e32 v67, v49, v69
	v_fmac_f32_e32 v81, v54, v66
	v_add_f32_e32 v66, v80, v67
	s_waitcnt lgkmcnt(0)
	v_mul_f32_e32 v67, v63, v77
	v_fmac_f32_e32 v81, v52, v68
	v_fmac_f32_e32 v67, v62, v76
	v_fmac_f32_e32 v81, v53, v69
	v_fmac_f32_e32 v67, v60, v78
	v_add_f32_e32 v65, v65, v81
	v_fmac_f32_e32 v67, v61, v79
	ds_read_b128 v[80:83], v74 offset:13312
	ds_read_b128 v[84:87], v74 offset:12288
	v_add_f32_e32 v65, v65, v67
	v_mul_f32_e32 v67, v59, v77
	v_fmac_f32_e32 v67, v58, v76
	v_fmac_f32_e32 v67, v56, v78
	v_fmac_f32_e32 v67, v57, v79
	v_add_f32_e32 v66, v66, v67
	s_waitcnt lgkmcnt(0)
	v_mul_f32_e32 v67, v43, v85
	v_fmac_f32_e32 v67, v42, v84
	v_mul_f32_e32 v69, v47, v81
	v_fmac_f32_e32 v67, v40, v86
	v_fmac_f32_e32 v69, v46, v80
	v_fmac_f32_e32 v67, v41, v87
	v_fmac_f32_e32 v69, v44, v82
	ds_read_b128 v[76:79], v74 offset:15360
	ds_read_b128 v[88:91], v74 offset:14336
	v_add_f32_e32 v67, 0, v67
	v_mul_f32_e32 v68, v7, v85
	v_fmac_f32_e32 v69, v45, v83
	v_fmac_f32_e32 v68, v6, v84
	v_add_f32_e32 v67, v69, v67
	v_mul_f32_e32 v69, v9, v81
	v_fmac_f32_e32 v68, v2, v86
	v_fmac_f32_e32 v69, v8, v80
	v_fmac_f32_e32 v68, v3, v87
	v_fmac_f32_e32 v69, v4, v82
	v_add_f32_e32 v68, 0, v68
	v_fmac_f32_e32 v69, v5, v83
	v_add_f32_e32 v68, v69, v68
	s_waitcnt lgkmcnt(0)
	v_mul_f32_e32 v69, v55, v89
	v_fmac_f32_e32 v69, v54, v88
	v_fmac_f32_e32 v69, v52, v90
	v_fmac_f32_e32 v69, v53, v91
	v_add_f32_e32 v67, v69, v67
	v_mul_f32_e32 v69, v51, v89
	v_fmac_f32_e32 v69, v50, v88
	v_fmac_f32_e32 v69, v48, v90
	v_fmac_f32_e32 v69, v49, v91
	v_add_f32_e32 v68, v69, v68
	v_mul_f32_e32 v69, v63, v77
	v_fmac_f32_e32 v69, v62, v76
	v_fmac_f32_e32 v69, v60, v78
	v_fmac_f32_e32 v69, v61, v79
	v_add_f32_e32 v67, v69, v67
	v_mul_f32_e32 v69, v59, v77
	v_fmac_f32_e32 v69, v58, v76
	v_fmac_f32_e32 v69, v56, v78
	v_fmac_f32_e32 v69, v57, v79
	v_add_f32_e32 v68, v69, v68
	ds_read_b128 v[76:79], v74 offset:16384
	ds_read_b128 v[80:83], v74 offset:17408
	s_waitcnt lgkmcnt(1)
	v_mul_f32_e32 v69, v43, v77
	v_mul_f32_e32 v77, v7, v77
	v_fmac_f32_e32 v69, v42, v76
	v_fmac_f32_e32 v77, v6, v76
	s_waitcnt lgkmcnt(0)
	v_mul_f32_e32 v76, v47, v81
	v_fmac_f32_e32 v69, v40, v78
	v_fmac_f32_e32 v76, v46, v80
	v_fmac_f32_e32 v77, v2, v78
	v_fmac_f32_e32 v69, v41, v79
	v_fmac_f32_e32 v76, v44, v82
	v_add_f32_e32 v69, 0, v69
	v_fmac_f32_e32 v77, v3, v79
	v_fmac_f32_e32 v76, v45, v83
	v_add_f32_e32 v84, 0, v77
	v_add_f32_e32 v69, v69, v76
	v_mul_f32_e32 v81, v9, v81
	ds_read_b128 v[76:79], v74 offset:18432
	v_fmac_f32_e32 v81, v8, v80
	v_fmac_f32_e32 v81, v4, v82
	v_fmac_f32_e32 v81, v5, v83
	v_add_f32_e32 v84, v84, v81
	ds_read_b128 v[80:83], v74 offset:19456
	s_waitcnt lgkmcnt(1)
	v_mul_f32_e32 v85, v55, v77
	v_mul_f32_e32 v77, v51, v77
	v_fmac_f32_e32 v77, v50, v76
	v_fmac_f32_e32 v77, v48, v78
	v_fmac_f32_e32 v77, v49, v79
	v_fmac_f32_e32 v85, v54, v76
	v_add_f32_e32 v76, v84, v77
	s_waitcnt lgkmcnt(0)
	v_mul_f32_e32 v77, v63, v81
	v_fmac_f32_e32 v85, v52, v78
	v_fmac_f32_e32 v77, v62, v80
	v_fmac_f32_e32 v85, v53, v79
	v_fmac_f32_e32 v77, v60, v82
	v_add_f32_e32 v69, v69, v85
	v_fmac_f32_e32 v77, v61, v83
	v_add_f32_e32 v69, v69, v77
	v_mul_f32_e32 v77, v59, v81
	v_fmac_f32_e32 v77, v58, v80
	ds_read_b128 v[78:81], v74 offset:21504
	ds_read_b128 v[84:87], v74 offset:20480
	v_fmac_f32_e32 v77, v56, v82
	ds_read_b128 v[88:91], v74 offset:23552
	ds_read_b128 v[92:95], v74 offset:22528
	v_fmac_f32_e32 v77, v57, v83
	s_waitcnt lgkmcnt(3)
	v_mul_f32_e32 v83, v47, v79
	s_waitcnt lgkmcnt(2)
	v_mul_f32_e32 v82, v7, v85
	v_fmac_f32_e32 v82, v6, v84
	v_mul_f32_e32 v79, v9, v79
	v_fmac_f32_e32 v82, v2, v86
	v_fmac_f32_e32 v79, v8, v78
	v_add_f32_e32 v76, v76, v77
	v_mul_f32_e32 v77, v43, v85
	v_fmac_f32_e32 v82, v3, v87
	v_fmac_f32_e32 v79, v4, v80
	v_fmac_f32_e32 v77, v42, v84
	v_add_f32_e32 v82, 0, v82
	v_fmac_f32_e32 v79, v5, v81
	v_fmac_f32_e32 v77, v40, v86
	v_fmac_f32_e32 v83, v46, v78
	v_add_f32_e32 v78, v79, v82
	s_waitcnt lgkmcnt(0)
	v_mul_f32_e32 v79, v55, v93
	v_fmac_f32_e32 v77, v41, v87
	v_fmac_f32_e32 v83, v44, v80
	v_fmac_f32_e32 v79, v54, v92
	v_add_f32_e32 v77, 0, v77
	v_fmac_f32_e32 v83, v45, v81
	v_fmac_f32_e32 v79, v52, v94
	v_add_f32_e32 v77, v83, v77
	v_fmac_f32_e32 v79, v53, v95
	v_add_f32_e32 v77, v79, v77
	v_mul_f32_e32 v79, v51, v93
	v_fmac_f32_e32 v79, v50, v92
	v_fmac_f32_e32 v79, v48, v94
	v_fmac_f32_e32 v79, v49, v95
	v_add_f32_e32 v78, v79, v78
	v_mul_f32_e32 v79, v63, v89
	v_fmac_f32_e32 v79, v62, v88
	v_fmac_f32_e32 v79, v60, v90
	v_fmac_f32_e32 v79, v61, v91
	v_add_f32_e32 v77, v79, v77
	v_mul_f32_e32 v79, v59, v89
	v_fmac_f32_e32 v79, v58, v88
	v_fmac_f32_e32 v79, v56, v90
	v_fmac_f32_e32 v79, v57, v91
	v_add_f32_e32 v78, v79, v78
	ds_read_b128 v[80:83], v74 offset:24576
	ds_read_b128 v[84:87], v74 offset:25600
	s_waitcnt lgkmcnt(1)
	v_mul_f32_e32 v79, v43, v81
	v_mul_f32_e32 v81, v7, v81
	v_fmac_f32_e32 v79, v42, v80
	v_fmac_f32_e32 v81, v6, v80
	s_waitcnt lgkmcnt(0)
	v_mul_f32_e32 v80, v47, v85
	v_fmac_f32_e32 v79, v40, v82
	v_fmac_f32_e32 v80, v46, v84
	v_fmac_f32_e32 v81, v2, v82
	v_fmac_f32_e32 v79, v41, v83
	v_fmac_f32_e32 v80, v44, v86
	v_add_f32_e32 v79, 0, v79
	v_fmac_f32_e32 v81, v3, v83
	v_fmac_f32_e32 v80, v45, v87
	v_add_f32_e32 v88, 0, v81
	v_add_f32_e32 v79, v79, v80
	v_mul_f32_e32 v85, v9, v85
	ds_read_b128 v[80:83], v74 offset:26624
	v_fmac_f32_e32 v85, v8, v84
	v_fmac_f32_e32 v85, v4, v86
	v_fmac_f32_e32 v85, v5, v87
	v_add_f32_e32 v88, v88, v85
	ds_read_b128 v[84:87], v74 offset:27648
	s_waitcnt lgkmcnt(1)
	v_mul_f32_e32 v89, v55, v81
	v_mul_f32_e32 v81, v51, v81
	v_fmac_f32_e32 v81, v50, v80
	v_fmac_f32_e32 v81, v48, v82
	v_fmac_f32_e32 v81, v49, v83
	v_fmac_f32_e32 v89, v54, v80
	v_add_f32_e32 v80, v88, v81
	s_waitcnt lgkmcnt(0)
	v_mul_f32_e32 v81, v63, v85
	v_fmac_f32_e32 v89, v52, v82
	v_fmac_f32_e32 v81, v62, v84
	v_fmac_f32_e32 v89, v53, v83
	v_fmac_f32_e32 v81, v60, v86
	v_add_f32_e32 v79, v79, v89
	v_fmac_f32_e32 v81, v61, v87
	v_add_f32_e32 v79, v79, v81
	v_mul_f32_e32 v81, v59, v85
	v_fmac_f32_e32 v81, v58, v84
	ds_read_b128 v[82:85], v74 offset:29696
	ds_read_b128 v[88:91], v74 offset:28672
	v_fmac_f32_e32 v81, v56, v86
	ds_read_b128 v[92:95], v74 offset:31744
	ds_read_b128 v[96:99], v74 offset:30720
	v_fmac_f32_e32 v81, v57, v87
	s_waitcnt lgkmcnt(3)
	v_mul_f32_e32 v87, v47, v83
	s_waitcnt lgkmcnt(2)
	v_mul_f32_e32 v86, v7, v89
	v_fmac_f32_e32 v86, v6, v88
	v_mul_f32_e32 v83, v9, v83
	v_fmac_f32_e32 v86, v2, v90
	v_fmac_f32_e32 v83, v8, v82
	v_add_f32_e32 v80, v80, v81
	v_mul_f32_e32 v81, v43, v89
	v_fmac_f32_e32 v86, v3, v91
	v_fmac_f32_e32 v83, v4, v84
	v_fmac_f32_e32 v81, v42, v88
	v_add_f32_e32 v86, 0, v86
	v_fmac_f32_e32 v83, v5, v85
	v_fmac_f32_e32 v81, v40, v90
	v_fmac_f32_e32 v87, v46, v82
	v_add_f32_e32 v82, v83, v86
	s_waitcnt lgkmcnt(0)
	v_mul_f32_e32 v83, v55, v97
	v_fmac_f32_e32 v81, v41, v91
	v_fmac_f32_e32 v87, v44, v84
	v_fmac_f32_e32 v83, v54, v96
	v_add_f32_e32 v81, 0, v81
	v_fmac_f32_e32 v87, v45, v85
	v_fmac_f32_e32 v83, v52, v98
	v_add_f32_e32 v81, v87, v81
	v_fmac_f32_e32 v83, v53, v99
	v_add_f32_e32 v81, v83, v81
	v_mul_f32_e32 v83, v51, v97
	v_fmac_f32_e32 v83, v50, v96
	v_fmac_f32_e32 v83, v48, v98
	v_fmac_f32_e32 v83, v49, v99
	v_add_f32_e32 v82, v83, v82
	v_mul_f32_e32 v83, v63, v93
	v_fmac_f32_e32 v83, v62, v92
	v_fmac_f32_e32 v83, v60, v94
	v_fmac_f32_e32 v83, v61, v95
	v_add_f32_e32 v81, v83, v81
	v_mul_f32_e32 v83, v59, v93
	v_fmac_f32_e32 v83, v58, v92
	v_fmac_f32_e32 v83, v56, v94
	v_fmac_f32_e32 v83, v57, v95
	v_add_f32_e32 v82, v83, v82
	ds_read_b128 v[84:87], v74 offset:32768
	ds_read_b128 v[88:91], v74 offset:33792
	s_waitcnt lgkmcnt(1)
	v_mul_f32_e32 v83, v43, v85
	v_mul_f32_e32 v85, v7, v85
	v_fmac_f32_e32 v83, v42, v84
	v_fmac_f32_e32 v85, v6, v84
	s_waitcnt lgkmcnt(0)
	v_mul_f32_e32 v84, v47, v89
	v_fmac_f32_e32 v83, v40, v86
	v_fmac_f32_e32 v84, v46, v88
	v_fmac_f32_e32 v85, v2, v86
	v_fmac_f32_e32 v83, v41, v87
	v_fmac_f32_e32 v84, v44, v90
	v_add_f32_e32 v83, 0, v83
	v_fmac_f32_e32 v85, v3, v87
	v_fmac_f32_e32 v84, v45, v91
	v_add_f32_e32 v92, 0, v85
	v_add_f32_e32 v83, v83, v84
	v_mul_f32_e32 v89, v9, v89
	ds_read_b128 v[84:87], v74 offset:34816
	v_fmac_f32_e32 v89, v8, v88
	v_fmac_f32_e32 v89, v4, v90
	v_fmac_f32_e32 v89, v5, v91
	v_add_f32_e32 v92, v92, v89
	ds_read_b128 v[88:91], v74 offset:35840
	s_waitcnt lgkmcnt(1)
	v_mul_f32_e32 v93, v55, v85
	v_mul_f32_e32 v85, v51, v85
	v_fmac_f32_e32 v85, v50, v84
	v_fmac_f32_e32 v85, v48, v86
	v_fmac_f32_e32 v85, v49, v87
	v_fmac_f32_e32 v93, v54, v84
	v_add_f32_e32 v84, v92, v85
	s_waitcnt lgkmcnt(0)
	v_mul_f32_e32 v85, v63, v89
	v_fmac_f32_e32 v93, v52, v86
	v_fmac_f32_e32 v85, v62, v88
	v_fmac_f32_e32 v93, v53, v87
	v_fmac_f32_e32 v85, v60, v90
	v_add_f32_e32 v83, v83, v93
	v_fmac_f32_e32 v85, v61, v91
	v_add_f32_e32 v83, v83, v85
	v_mul_f32_e32 v85, v59, v89
	v_fmac_f32_e32 v85, v58, v88
	ds_read_b128 v[86:89], v74 offset:37888
	ds_read_b128 v[92:95], v74 offset:36864
	v_fmac_f32_e32 v85, v56, v90
	ds_read_b128 v[96:99], v74 offset:39936
	ds_read_b128 v[100:103], v74 offset:38912
	v_fmac_f32_e32 v85, v57, v91
	s_waitcnt lgkmcnt(3)
	v_mul_f32_e32 v91, v47, v87
	s_waitcnt lgkmcnt(2)
	v_mul_f32_e32 v90, v7, v93
	v_fmac_f32_e32 v90, v6, v92
	v_mul_f32_e32 v87, v9, v87
	v_fmac_f32_e32 v90, v2, v94
	v_fmac_f32_e32 v87, v8, v86
	v_add_f32_e32 v84, v84, v85
	v_mul_f32_e32 v85, v43, v93
	v_fmac_f32_e32 v90, v3, v95
	v_fmac_f32_e32 v87, v4, v88
	v_fmac_f32_e32 v85, v42, v92
	v_add_f32_e32 v90, 0, v90
	v_fmac_f32_e32 v87, v5, v89
	v_fmac_f32_e32 v85, v40, v94
	v_fmac_f32_e32 v91, v46, v86
	v_add_f32_e32 v86, v87, v90
	s_waitcnt lgkmcnt(0)
	v_mul_f32_e32 v87, v55, v101
	v_fmac_f32_e32 v85, v41, v95
	v_fmac_f32_e32 v91, v44, v88
	v_fmac_f32_e32 v87, v54, v100
	v_add_f32_e32 v85, 0, v85
	v_fmac_f32_e32 v91, v45, v89
	v_fmac_f32_e32 v87, v52, v102
	v_add_f32_e32 v85, v91, v85
	v_fmac_f32_e32 v87, v53, v103
	v_add_f32_e32 v85, v87, v85
	v_mul_f32_e32 v87, v51, v101
	v_fmac_f32_e32 v87, v50, v100
	v_fmac_f32_e32 v87, v48, v102
	v_fmac_f32_e32 v87, v49, v103
	v_add_f32_e32 v86, v87, v86
	v_mul_f32_e32 v87, v63, v97
	v_fmac_f32_e32 v87, v62, v96
	v_fmac_f32_e32 v87, v60, v98
	v_fmac_f32_e32 v87, v61, v99
	v_add_f32_e32 v85, v87, v85
	v_mul_f32_e32 v87, v59, v97
	v_fmac_f32_e32 v87, v58, v96
	v_fmac_f32_e32 v87, v56, v98
	v_fmac_f32_e32 v87, v57, v99
	v_add_f32_e32 v86, v87, v86
	ds_read_b128 v[88:91], v74 offset:40960
	ds_read_b128 v[92:95], v74 offset:41984
	s_waitcnt lgkmcnt(1)
	v_mul_f32_e32 v87, v43, v89
	v_mul_f32_e32 v89, v7, v89
	v_fmac_f32_e32 v87, v42, v88
	v_fmac_f32_e32 v89, v6, v88
	s_waitcnt lgkmcnt(0)
	v_mul_f32_e32 v88, v47, v93
	v_fmac_f32_e32 v87, v40, v90
	v_fmac_f32_e32 v88, v46, v92
	v_mul_f32_e32 v93, v9, v93
	v_fmac_f32_e32 v89, v2, v90
	v_fmac_f32_e32 v87, v41, v91
	v_fmac_f32_e32 v88, v44, v94
	v_fmac_f32_e32 v93, v8, v92
	v_add_f32_e32 v87, 0, v87
	v_fmac_f32_e32 v89, v3, v91
	v_fmac_f32_e32 v88, v45, v95
	v_fmac_f32_e32 v93, v4, v94
	v_add_f32_e32 v96, 0, v89
	v_add_f32_e32 v87, v87, v88
	ds_read_b128 v[88:91], v74 offset:43008
	v_fmac_f32_e32 v93, v5, v95
	v_add_f32_e32 v96, v96, v93
	ds_read_b128 v[92:95], v74 offset:44032
	s_waitcnt lgkmcnt(1)
	v_mul_f32_e32 v97, v55, v89
	v_mul_f32_e32 v89, v51, v89
	v_fmac_f32_e32 v97, v54, v88
	v_fmac_f32_e32 v89, v50, v88
	s_waitcnt lgkmcnt(0)
	v_mul_f32_e32 v88, v63, v93
	v_fmac_f32_e32 v97, v52, v90
	v_fmac_f32_e32 v88, v62, v92
	v_fmac_f32_e32 v97, v53, v91
	v_fmac_f32_e32 v89, v48, v90
	v_fmac_f32_e32 v88, v60, v94
	v_add_f32_e32 v87, v87, v97
	v_fmac_f32_e32 v89, v49, v91
	v_fmac_f32_e32 v88, v61, v95
	v_add_f32_e32 v100, v96, v89
	v_add_f32_e32 v87, v87, v88
	ds_read_b128 v[88:91], v74 offset:46080
	ds_read_b128 v[96:99], v74 offset:45056
	v_mul_f32_e32 v93, v59, v93
	v_fmac_f32_e32 v93, v58, v92
	v_fmac_f32_e32 v93, v56, v94
	v_fmac_f32_e32 v93, v57, v95
	s_waitcnt lgkmcnt(0)
	v_mul_f32_e32 v105, v43, v97
	v_mul_f32_e32 v97, v7, v97
	v_add_f32_e32 v104, v100, v93
	ds_read_b128 v[92:95], v74 offset:48128
	ds_read_b128 v[100:103], v74 offset:47104
	v_fmac_f32_e32 v97, v6, v96
	v_fmac_f32_e32 v97, v2, v98
	v_fmac_f32_e32 v97, v3, v99
	v_fmac_f32_e32 v105, v42, v96
	v_add_f32_e32 v96, 0, v97
	v_mul_f32_e32 v97, v47, v89
	v_mul_f32_e32 v89, v9, v89
	v_fmac_f32_e32 v97, v46, v88
	v_fmac_f32_e32 v89, v8, v88
	v_fmac_f32_e32 v97, v44, v90
	v_fmac_f32_e32 v89, v4, v90
	s_waitcnt lgkmcnt(0)
	v_mul_f32_e32 v90, v51, v101
	v_fmac_f32_e32 v90, v50, v100
	v_fmac_f32_e32 v89, v5, v91
	v_fmac_f32_e32 v90, v48, v102
	v_fmac_f32_e32 v105, v40, v98
	v_add_f32_e32 v88, v89, v96
	v_mul_f32_e32 v89, v55, v101
	v_fmac_f32_e32 v90, v49, v103
	v_fmac_f32_e32 v105, v41, v99
	v_fmac_f32_e32 v89, v54, v100
	v_add_f32_e32 v88, v90, v88
	v_mul_f32_e32 v90, v63, v93
	v_add_f32_e32 v105, 0, v105
	v_fmac_f32_e32 v97, v45, v91
	v_fmac_f32_e32 v89, v52, v102
	v_fmac_f32_e32 v90, v62, v92
	v_add_f32_e32 v97, v97, v105
	v_fmac_f32_e32 v89, v53, v103
	v_fmac_f32_e32 v90, v60, v94
	v_add_f32_e32 v89, v89, v97
	v_fmac_f32_e32 v90, v61, v95
	v_add_f32_e32 v105, v90, v89
	v_mul_f32_e32 v89, v59, v93
	v_fmac_f32_e32 v89, v58, v92
	v_fmac_f32_e32 v89, v56, v94
	v_fmac_f32_e32 v89, v57, v95
	v_add_f32_e32 v106, v89, v88
	ds_read_b128 v[88:91], v74 offset:49152
	ds_read_b128 v[92:95], v74 offset:50176
	s_waitcnt lgkmcnt(1)
	v_mul_f32_e32 v96, v43, v89
	v_mul_f32_e32 v89, v7, v89
	v_fmac_f32_e32 v96, v42, v88
	v_fmac_f32_e32 v89, v6, v88
	v_fmac_f32_e32 v96, v40, v90
	v_fmac_f32_e32 v89, v2, v90
	v_fmac_f32_e32 v96, v41, v91
	v_fmac_f32_e32 v89, v3, v91
	v_add_f32_e32 v88, 0, v96
	v_add_f32_e32 v96, 0, v89
	s_waitcnt lgkmcnt(0)
	v_mul_f32_e32 v89, v47, v93
	v_fmac_f32_e32 v89, v46, v92
	v_mul_f32_e32 v93, v9, v93
	v_fmac_f32_e32 v89, v44, v94
	v_fmac_f32_e32 v93, v8, v92
	v_fmac_f32_e32 v89, v45, v95
	v_fmac_f32_e32 v93, v4, v94
	v_add_f32_e32 v97, v88, v89
	ds_read_b128 v[88:91], v74 offset:51200
	v_fmac_f32_e32 v93, v5, v95
	v_add_f32_e32 v96, v96, v93
	ds_read_b128 v[92:95], v74 offset:52224
	s_waitcnt lgkmcnt(1)
	v_mul_f32_e32 v98, v55, v89
	v_mul_f32_e32 v89, v51, v89
	v_fmac_f32_e32 v98, v54, v88
	v_fmac_f32_e32 v89, v50, v88
	s_waitcnt lgkmcnt(0)
	v_mul_f32_e32 v88, v63, v93
	v_fmac_f32_e32 v98, v52, v90
	v_fmac_f32_e32 v88, v62, v92
	v_fmac_f32_e32 v98, v53, v91
	v_fmac_f32_e32 v89, v48, v90
	v_fmac_f32_e32 v88, v60, v94
	v_add_f32_e32 v97, v97, v98
	v_fmac_f32_e32 v89, v49, v91
	v_fmac_f32_e32 v88, v61, v95
	v_add_f32_e32 v100, v96, v89
	v_add_f32_e32 v107, v97, v88
	ds_read_b128 v[88:91], v74 offset:54272
	ds_read_b128 v[96:99], v74 offset:53248
	v_mul_f32_e32 v93, v59, v93
	v_fmac_f32_e32 v93, v58, v92
	v_fmac_f32_e32 v93, v56, v94
	v_fmac_f32_e32 v93, v57, v95
	s_waitcnt lgkmcnt(0)
	v_mul_f32_e32 v109, v43, v97
	v_mul_f32_e32 v97, v7, v97
	v_add_f32_e32 v108, v100, v93
	ds_read_b128 v[92:95], v74 offset:56320
	ds_read_b128 v[100:103], v74 offset:55296
	v_fmac_f32_e32 v97, v6, v96
	v_fmac_f32_e32 v97, v2, v98
	v_fmac_f32_e32 v97, v3, v99
	v_fmac_f32_e32 v109, v42, v96
	v_add_f32_e32 v96, 0, v97
	v_mul_f32_e32 v97, v47, v89
	v_mul_f32_e32 v89, v9, v89
	v_fmac_f32_e32 v97, v46, v88
	v_fmac_f32_e32 v89, v8, v88
	v_fmac_f32_e32 v97, v44, v90
	v_fmac_f32_e32 v89, v4, v90
	s_waitcnt lgkmcnt(0)
	v_mul_f32_e32 v90, v51, v101
	v_fmac_f32_e32 v90, v50, v100
	v_fmac_f32_e32 v89, v5, v91
	v_fmac_f32_e32 v90, v48, v102
	v_fmac_f32_e32 v109, v40, v98
	v_add_f32_e32 v88, v89, v96
	v_mul_f32_e32 v89, v55, v101
	v_fmac_f32_e32 v90, v49, v103
	v_fmac_f32_e32 v109, v41, v99
	v_fmac_f32_e32 v89, v54, v100
	v_add_f32_e32 v88, v90, v88
	v_mul_f32_e32 v90, v63, v93
	v_add_f32_e32 v109, 0, v109
	v_fmac_f32_e32 v97, v45, v91
	v_fmac_f32_e32 v89, v52, v102
	v_fmac_f32_e32 v90, v62, v92
	v_add_f32_e32 v97, v97, v109
	v_fmac_f32_e32 v89, v53, v103
	v_fmac_f32_e32 v90, v60, v94
	v_add_f32_e32 v89, v89, v97
	v_fmac_f32_e32 v90, v61, v95
	v_add_f32_e32 v109, v90, v89
	v_mul_f32_e32 v89, v59, v93
	v_fmac_f32_e32 v89, v58, v92
	v_fmac_f32_e32 v89, v56, v94
	v_fmac_f32_e32 v89, v57, v95
	v_add_f32_e32 v110, v89, v88
	ds_read_b128 v[88:91], v74 offset:57344
	ds_read_b128 v[92:95], v74 offset:58368
	s_waitcnt lgkmcnt(1)
	v_mul_f32_e32 v96, v43, v89
	v_mul_f32_e32 v89, v7, v89
	v_fmac_f32_e32 v96, v42, v88
	v_fmac_f32_e32 v89, v6, v88
	v_fmac_f32_e32 v96, v40, v90
	v_fmac_f32_e32 v89, v2, v90
	v_fmac_f32_e32 v96, v41, v91
	v_fmac_f32_e32 v89, v3, v91
	v_add_f32_e32 v88, 0, v96
	v_add_f32_e32 v96, 0, v89
	s_waitcnt lgkmcnt(0)
	v_mul_f32_e32 v89, v47, v93
	v_fmac_f32_e32 v89, v46, v92
	v_mul_f32_e32 v93, v9, v93
	v_fmac_f32_e32 v89, v44, v94
	v_fmac_f32_e32 v93, v8, v92
	v_fmac_f32_e32 v89, v45, v95
	v_fmac_f32_e32 v93, v4, v94
	v_add_f32_e32 v97, v88, v89
	ds_read_b128 v[88:91], v74 offset:59392
	v_fmac_f32_e32 v93, v5, v95
	v_add_f32_e32 v96, v96, v93
	ds_read_b128 v[92:95], v74 offset:60416
	s_waitcnt lgkmcnt(1)
	v_mul_f32_e32 v98, v55, v89
	v_mul_f32_e32 v89, v51, v89
	v_fmac_f32_e32 v98, v54, v88
	v_fmac_f32_e32 v89, v50, v88
	s_waitcnt lgkmcnt(0)
	v_mul_f32_e32 v88, v63, v93
	v_fmac_f32_e32 v98, v52, v90
	v_fmac_f32_e32 v88, v62, v92
	v_fmac_f32_e32 v98, v53, v91
	v_fmac_f32_e32 v89, v48, v90
	v_fmac_f32_e32 v88, v60, v94
	v_add_f32_e32 v97, v97, v98
	v_fmac_f32_e32 v89, v49, v91
	v_fmac_f32_e32 v88, v61, v95
	v_add_f32_e32 v100, v96, v89
	v_add_f32_e32 v111, v97, v88
	v_mul_f32_e32 v93, v59, v93
	ds_read_b128 v[88:91], v74 offset:62464
	ds_read_b128 v[96:99], v74 offset:61440
	v_fmac_f32_e32 v93, v58, v92
	v_fmac_f32_e32 v93, v56, v94
	v_fmac_f32_e32 v93, v57, v95
	v_add_f32_e32 v112, v100, v93
	ds_read_b128 v[92:95], v74 offset:64512
	ds_read_b128 v[100:103], v74 offset:63488
	s_waitcnt lgkmcnt(2)
	v_mul_f32_e32 v7, v7, v97
	v_fmac_f32_e32 v7, v6, v96
	v_mul_f32_e32 v43, v43, v97
	v_fmac_f32_e32 v7, v2, v98
	v_mul_f32_e32 v6, v9, v89
	v_fmac_f32_e32 v43, v42, v96
	v_fmac_f32_e32 v7, v3, v99
	v_mul_f32_e32 v3, v47, v89
	v_fmac_f32_e32 v6, v8, v88
	v_fmac_f32_e32 v43, v40, v98
	v_fmac_f32_e32 v3, v46, v88
	v_fmac_f32_e32 v6, v4, v90
	s_waitcnt lgkmcnt(0)
	v_mul_f32_e32 v4, v55, v101
	v_fmac_f32_e32 v43, v41, v99
	v_fmac_f32_e32 v3, v44, v90
	v_fmac_f32_e32 v4, v54, v100
	v_add_f32_e32 v40, 0, v43
	v_fmac_f32_e32 v3, v45, v91
	v_fmac_f32_e32 v4, v52, v102
	v_add_f32_e32 v3, v3, v40
	v_fmac_f32_e32 v4, v53, v103
	v_add_f32_e32 v3, v4, v3
	v_mul_f32_e32 v4, v51, v101
	v_fmac_f32_e32 v4, v50, v100
	v_add_f32_e32 v2, 0, v7
	v_fmac_f32_e32 v6, v5, v91
	v_fmac_f32_e32 v4, v48, v102
	v_add_f32_e32 v2, v6, v2
	v_fmac_f32_e32 v4, v49, v103
	v_add_f32_e32 v2, v4, v2
	v_mul_f32_e32 v4, v63, v93
	v_fmac_f32_e32 v4, v62, v92
	v_fmac_f32_e32 v4, v60, v94
	v_fmac_f32_e32 v4, v61, v95
	v_add_f32_e32 v3, v4, v3
	v_mul_f32_e32 v4, v59, v93
	v_fmac_f32_e32 v4, v58, v92
	v_fmac_f32_e32 v4, v56, v94
	v_fmac_f32_e32 v4, v57, v95
	v_add_f32_e32 v2, v4, v2
	v_cndmask_b32_e64 v4, v12, v64, s[0:1]
	ds_bpermute_b32 v4, v1, v4
	v_cndmask_b32_e64 v5, v64, v12, s[0:1]
	v_cndmask_b32_e64 v7, v11, v39, s[0:1]
	ds_bpermute_b32 v7, v1, v7
	v_cndmask_b32_e64 v8, v67, v68, s[0:1]
	s_waitcnt lgkmcnt(1)
	v_add_f32_e32 v4, v5, v4
	v_cndmask_b32_e64 v5, v65, v66, s[0:1]
	ds_bpermute_b32 v5, v1, v5
	ds_bpermute_b32 v8, v1, v8
	v_cndmask_b32_e64 v9, v69, v76, s[0:1]
	v_cndmask_b32_e64 v6, v39, v11, s[0:1]
	ds_bpermute_b32 v9, v1, v9
	v_cndmask_b32_e64 v11, v77, v78, s[0:1]
	ds_bpermute_b32 v11, v1, v11
	v_cndmask_b32_e64 v12, v79, v80, s[0:1]
	s_waitcnt lgkmcnt(4)
	v_add_f32_e32 v6, v6, v7
	v_cndmask_b32_e64 v7, v66, v65, s[0:1]
	ds_bpermute_b32 v12, v1, v12
	v_cndmask_b32_e64 v39, v81, v82, s[0:1]
	s_waitcnt lgkmcnt(4)
	v_add_f32_e32 v5, v7, v5
	v_cndmask_b32_e64 v7, v68, v67, s[0:1]
	ds_bpermute_b32 v39, v1, v39
	v_cndmask_b32_e64 v40, v83, v84, s[0:1]
	s_waitcnt lgkmcnt(4)
	v_add_f32_e32 v7, v7, v8
	v_cndmask_b32_e64 v8, v76, v69, s[0:1]
	ds_bpermute_b32 v40, v1, v40
	v_cndmask_b32_e64 v41, v85, v86, s[0:1]
	s_waitcnt lgkmcnt(4)
	v_add_f32_e32 v8, v8, v9
	v_cndmask_b32_e64 v9, v78, v77, s[0:1]
	ds_bpermute_b32 v41, v1, v41
	s_waitcnt lgkmcnt(4)
	v_add_f32_e32 v9, v9, v11
	v_cndmask_b32_e64 v11, v80, v79, s[0:1]
	s_waitcnt lgkmcnt(3)
	v_add_f32_e32 v11, v11, v12
	v_cndmask_b32_e64 v12, v82, v81, s[0:1]
	s_waitcnt lgkmcnt(2)
	v_add_f32_e32 v12, v12, v39
	v_cndmask_b32_e64 v39, v84, v83, s[0:1]
	v_cndmask_b32_e64 v42, v87, v104, s[0:1]
	s_waitcnt lgkmcnt(1)
	v_add_f32_e32 v39, v39, v40
	v_cndmask_b32_e64 v40, v86, v85, s[0:1]
	ds_bpermute_b32 v42, v1, v42
	v_cndmask_b32_e64 v43, v105, v106, s[0:1]
	s_waitcnt lgkmcnt(1)
	v_add_f32_e32 v40, v40, v41
	ds_bpermute_b32 v43, v1, v43
	v_cndmask_b32_e64 v44, v107, v108, s[0:1]
	v_cndmask_b32_e64 v47, v3, v2, s[0:1]
	v_cndmask_b32_e64 v2, v2, v3, s[0:1]
	v_cndmask_b32_e64 v3, v39, v4, s[6:7]
	v_cndmask_b32_e64 v4, v4, v39, s[6:7]
	ds_bpermute_b32 v44, v1, v44
	ds_bpermute_b32 v4, v37, v4
	v_cndmask_b32_e64 v39, v6, v40, s[6:7]
	ds_bpermute_b32 v39, v37, v39
	v_cndmask_b32_e64 v41, v104, v87, s[0:1]
	s_waitcnt lgkmcnt(4)
	v_add_f32_e32 v41, v41, v42
	v_cndmask_b32_e64 v42, v106, v105, s[0:1]
	s_waitcnt lgkmcnt(3)
	v_add_f32_e32 v42, v42, v43
	v_cndmask_b32_e64 v43, v108, v107, s[0:1]
	v_cndmask_b32_e64 v45, v109, v110, s[0:1]
	s_waitcnt lgkmcnt(2)
	v_add_f32_e32 v43, v43, v44
	ds_bpermute_b32 v45, v1, v45
	v_cndmask_b32_e64 v46, v111, v112, s[0:1]
	s_waitcnt lgkmcnt(2)
	v_add_f32_e32 v3, v3, v4
	v_cndmask_b32_e64 v4, v40, v6, s[6:7]
	v_cndmask_b32_e64 v6, v42, v7, s[6:7]
	v_cndmask_b32_e64 v7, v7, v42, s[6:7]
	ds_bpermute_b32 v46, v1, v46
	ds_bpermute_b32 v47, v1, v47
	s_waitcnt lgkmcnt(3)
	v_add_f32_e32 v4, v4, v39
	ds_bpermute_b32 v7, v37, v7
	v_cndmask_b32_e64 v39, v8, v43, s[6:7]
	ds_bpermute_b32 v39, v37, v39
	v_cndmask_b32_e64 v44, v110, v109, s[0:1]
	s_waitcnt lgkmcnt(4)
	v_add_f32_e32 v44, v44, v45
	v_cndmask_b32_e64 v45, v112, v111, s[0:1]
	s_waitcnt lgkmcnt(3)
	v_add_f32_e32 v45, v45, v46
	s_waitcnt lgkmcnt(2)
	v_add_f32_e32 v2, v2, v47
	s_waitcnt lgkmcnt(1)
	v_add_f32_e32 v6, v6, v7
	v_cndmask_b32_e64 v7, v43, v8, s[6:7]
	v_cndmask_b32_e64 v46, v5, v41, s[6:7]
	v_cndmask_b32_e64 v40, v9, v44, s[6:7]
	s_waitcnt lgkmcnt(0)
	v_add_f32_e32 v7, v7, v39
	v_cndmask_b32_e64 v8, v44, v9, s[6:7]
	v_cndmask_b32_e64 v9, v45, v11, s[6:7]
	v_cndmask_b32_e64 v11, v11, v45, s[6:7]
	v_cndmask_b32_e64 v39, v12, v2, s[6:7]
	ds_bpermute_b32 v46, v37, v46
	ds_bpermute_b32 v40, v37, v40
	ds_bpermute_b32 v11, v37, v11
	ds_bpermute_b32 v39, v37, v39
	v_cndmask_b32_e64 v5, v41, v5, s[6:7]
	v_cndmask_b32_e64 v2, v2, v12, s[6:7]
	s_waitcnt lgkmcnt(3)
	v_add_f32_e32 v5, v5, v46
	s_waitcnt lgkmcnt(2)
	v_add_f32_e32 v8, v8, v40
	s_waitcnt lgkmcnt(1)
	v_add_f32_e32 v9, v9, v11
	s_waitcnt lgkmcnt(0)
	v_add_f32_e32 v2, v2, v39
	v_cndmask_b32_e64 v40, v3, v7, s[8:9]
	v_cndmask_b32_e64 v3, v7, v3, s[8:9]
	v_cndmask_b32_e64 v7, v8, v4, s[8:9]
	v_cndmask_b32_e64 v4, v4, v8, s[8:9]
	v_cndmask_b32_e64 v8, v5, v9, s[8:9]
	v_cndmask_b32_e64 v11, v6, v2, s[8:9]
	ds_bpermute_b32 v40, v70, v40
	ds_bpermute_b32 v4, v70, v4
	ds_bpermute_b32 v8, v70, v8
	ds_bpermute_b32 v11, v70, v11
	v_cndmask_b32_e64 v5, v9, v5, s[8:9]
	v_cndmask_b32_e64 v2, v2, v6, s[8:9]
	s_waitcnt lgkmcnt(3)
	v_add_f32_e32 v3, v3, v40
	s_waitcnt lgkmcnt(2)
	v_add_f32_e32 v4, v7, v4
	s_waitcnt lgkmcnt(1)
	v_add_f32_e32 v5, v5, v8
	s_waitcnt lgkmcnt(0)
	v_add_f32_e32 v2, v2, v11
	v_cndmask_b32_e64 v6, v3, v5, s[10:11]
	v_cndmask_b32_e64 v7, v4, v2, s[10:11]
	ds_bpermute_b32 v6, v71, v6
	ds_bpermute_b32 v7, v71, v7
	v_cndmask_b32_e64 v3, v5, v3, s[10:11]
	v_cndmask_b32_e64 v2, v2, v4, s[10:11]
	s_waitcnt lgkmcnt(1)
	v_add_f32_e32 v3, v3, v6
	s_waitcnt lgkmcnt(0)
	v_add_f32_e32 v2, v2, v7
	v_cndmask_b32_e64 v4, v3, v2, s[12:13]
	ds_bpermute_b32 v4, v72, v4
	v_cndmask_b32_e64 v2, v2, v3, s[12:13]
	s_waitcnt lgkmcnt(0)
	v_add_f32_e32 v2, v2, v4
	ds_bpermute_b32 v3, v73, v2
	s_waitcnt lgkmcnt(0)
	v_add_f32_e32 v2, v2, v3
	ds_bpermute_b32 v3, v72, v2
	s_waitcnt lgkmcnt(0)
	v_max_f32_e32 v3, v3, v3
	v_max_f32_e32 v3, v2, v3
	ds_bpermute_b32 v4, v71, v3
	s_waitcnt lgkmcnt(0)
	v_max_f32_e32 v4, v4, v4
	v_max_f32_e32 v3, v3, v4
	ds_bpermute_b32 v4, v70, v3
	s_waitcnt lgkmcnt(0)
	v_max_f32_e32 v4, v4, v4
	v_max_f32_e32 v3, v3, v4
	ds_bpermute_b32 v4, v37, v3
	s_waitcnt lgkmcnt(0)
	v_max_f32_e32 v4, v4, v4
	v_max_f32_e32 v3, v3, v4
	v_sub_f32_e32 v2, v2, v3
	v_mul_f32_e32 v2, 0x3fb8aa3b, v2
	v_exp_f32_e32 v2, v2
	ds_bpermute_b32 v3, v72, v2
	s_waitcnt lgkmcnt(0)
	v_add_f32_e32 v3, v2, v3
	ds_bpermute_b32 v4, v71, v3
	s_waitcnt lgkmcnt(0)
	v_add_f32_e32 v3, v3, v4
	ds_bpermute_b32 v4, v70, v3
	s_waitcnt lgkmcnt(0)
	v_add_f32_e32 v3, v3, v4
	ds_bpermute_b32 v4, v37, v3
	s_and_saveexec_b64 s[4:5], s[14:15]
	s_cbranch_execz .LBB0_1229
	s_waitcnt lgkmcnt(0)
	v_add_f32_e32 v3, v3, v4
	v_div_scale_f32 v4, s[30:31], v3, v3, v2
	v_rcp_f32_e32 v5, v4
	v_ashrrev_i32_e32 v39, 31, v38
	v_and_or_b32 v6, v10, s27, v75
	v_lshlrev_b32_e32 v12, 2, v6
	v_fma_f32 v7, -v4, v5, 1.0
	v_fmac_f32_e32 v5, v7, v5
	v_div_scale_f32 v7, vcc, v2, v3, v2
	v_mul_f32_e32 v8, v7, v5
	v_fma_f32 v9, -v4, v8, v7
	v_fmac_f32_e32 v8, v9, v5
	v_fma_f32 v4, -v4, v8, v7
	v_div_fmas_f32 v4, v4, v5, v8
	v_div_fixup_f32 v4, v4, v3, v2
	v_lshlrev_b64 v[2:3], 18, v[38:39]
	v_lshl_add_u64 v[2:3], v[24:25], 0, v[2:3]
	v_lshl_add_u64 v[2:3], v[2:3], 0, v[12:13]
	global_store_dword v[2:3], v4, off
	s_branch .LBB0_1229
